# L slot interleave with reads leading each DMA (3 ds_read_b128 then 1 LDS-DMA)
# speedup vs baseline: 1.0786x; 1.0012x over previous
; #define PG8_STAGE(bufoff, gbase, voff) do { _Pragma("unroll") for (int _i = 0; _i < 2; ++_i) \
;         __builtin_amdgcn_global_load_lds((const unsigned*)((const char*)(gbase) + (voff)[_i]), (PG8_LAS unsigned*)(lds + (bufoff) + ldsw + _i * 8192), 16, 0, 0); } while (0)
; #define PG8_LDA(dst, b, h) do { _Pragma("unroll") for (int m = 0; m < 4; ++m) _Pragma("unroll") for (int k = 0; k < 2; ++k) dst[m][k] = *(const PG8_LAS bf16x8*)(lds + PG8_SA(b, h) + aoff + m * 2048 + k * 1024); } while (0)
; #define PG8_LDB(dst, b, h) do { _Pragma("unroll") for (int n = 0; n < 2; ++n) _Pragma("unroll") for (int k = 0; k < 2; ++k) dst[n][k] = *(const PG8_LAS bf16x8*)(lds + PG8_SB(b, h) + boff + n * 2048 + k * 1024); } while (0)
; #define PG8_MMA(ai, bj, At, Bt) do { __builtin_amdgcn_s_setprio(1); _Pragma("unroll") for (int m = 0; m < 4; ++m) _Pragma("unroll") for (int n = 0; n < 2; ++n) _Pragma("unroll") for (int k = 0; k < 2; ++k) \
;         acc[ai][bj][m][n] = __builtin_amdgcn_mfma_f32_16x16x32_bf16(Bt[n][k], At[m][k], acc[ai][bj][m][n], 0, 0, 0); __builtin_amdgcn_s_setprio(0); } while (0)
; #define PG8_WAIT_V(n) asm volatile("s_waitcnt vmcnt(" #n ")" ::: "memory")
; #define PG8_WAIT_L(n) asm volatile("s_waitcnt lgkmcnt(" #n ")" ::: "memory")
; #define PG8_BAR __builtin_amdgcn_s_barrier()
; #define PG8_SCHED __builtin_amdgcn_sched_barrier(0)
; template <class Epi, class Sched, bool ALIGN_EPI>
; __device__ __forceinline__ void gemm_phase(PG8_LAS unsigned char* lds, const Gemm g, const Sched& S, const Epi& E) {
;     ...
;             PG8_LDB(B0, 0, 0); PG8_LDB(B1, 0, 1); PG8_SCHED; PG8_LDA(At, 0, 0); PG8_STAGE(PG8_SA(1, 1), a1 + hstepA, voffA);
;             PG8_WAIT_V(8); PG8_WAIT_L(0); PG8_BAR; PG8_MMA(0, 0, At, B0); PG8_MMA(0, 1, At, B1); PG8_BAR; PG8_SCHED;
;             PG8_LDA(At, 0, 1); PG8_STAGE(PG8_SB(0, 0), b2, voffB); PG8_STAGE(PG8_SB(0, 1), b2 + hstepB, voffB); PG8_STAGE(PG8_SA(0, 0), a2, voffA);
;             PG8_WAIT_V(8); PG8_WAIT_L(0); PG8_BAR; PG8_MMA(1, 0, At, B0); PG8_MMA(1, 1, At, B1); PG8_BAR; PG8_SCHED;
.Lp8k_A_loop:
	ds_read_b128 v[190:193], v155 offset:0
	ds_read_b128 v[194:197], v155 offset:1024
	ds_read_b128 v[198:201], v155 offset:2048
	s_add_i32 m0, s2, 0x18000
	s_nop 0
	global_load_lds_dwordx4 v134, s[28:29]
	ds_read_b128 v[202:205], v155 offset:3072
	ds_read_b128 v[206:209], v155 offset:4096
	ds_read_b128 v[210:213], v155 offset:5120
	s_add_i32 m0, s2, 0x1a000
	s_nop 0
	global_load_lds_dwordx4 v130, s[28:29]
	ds_read_b128 v[214:217], v155 offset:6144
	ds_read_b128 v[218:221], v155 offset:7168
	ds_read_b128 v[156:159], v153 offset:0
	s_add_u32 s30, s28, 0x20000
	s_addc_u32 s31, s29, 0
	s_add_i32 m0, s2, 0x19000
	s_nop 0
	global_load_lds_dwordx4 v134, s[30:31]
	ds_read_b128 v[160:163], v153 offset:1024
	ds_read_b128 v[164:167], v153 offset:2048
	ds_read_b128 v[168:171], v153 offset:3072
	s_add_i32 m0, s2, 0x1b000
	s_nop 0
	global_load_lds_dwordx4 v130, s[30:31]
	ds_read_b128 v[174:177], v153 offset:16384
	ds_read_b128 v[178:181], v153 offset:17408
	ds_read_b128 v[182:185], v153 offset:18432
	s_add_u32 s30, s28, 0x80000
	s_addc_u32 s31, s29, 0
	s_add_i32 m0, s2, 0x1c000
	s_nop 0
	global_load_lds_dwordx4 v134, s[30:31]
	ds_read_b128 v[186:189], v153 offset:19456
	ds_read_b128 v[222:225], v155 offset:16384
	ds_read_b128 v[226:229], v155 offset:17408
	s_add_i32 m0, s2, 0x1e000
	s_nop 0
	global_load_lds_dwordx4 v130, s[30:31]
	ds_read_b128 v[230:233], v155 offset:18432
	ds_read_b128 v[234:237], v155 offset:19456
	ds_read_b128 v[238:241], v155 offset:20480
	s_add_u32 s30, s28, 0xa0000
	s_addc_u32 s31, s29, 0
	s_add_i32 m0, s2, 0x1d000
	s_nop 0
	global_load_lds_dwordx4 v134, s[30:31]
	ds_read_b128 v[242:245], v155 offset:21504
	ds_read_b128 v[246:249], v155 offset:22528
	ds_read_b128 v[250:253], v155 offset:23552
	s_add_i32 m0, s2, 0x1f000
	s_nop 0
	global_load_lds_dwordx4 v130, s[30:31]
	s_add_u32 s28, s28, 0x80
	s_addc_u32 s29, s29, 0
	s_waitcnt vmcnt(8) lgkmcnt(0)
	s_barrier
	s_setprio 1
	v_mfma_f32_16x16x32_bf16 v[126:129], v[156:159], v[190:193], v[126:129]
	v_mfma_f32_16x16x32_bf16 v[126:129], v[160:163], v[194:197], v[126:129]
	v_mfma_f32_16x16x32_bf16 v[122:125], v[168:171], v[194:197], v[122:125]
	v_mfma_f32_16x16x32_bf16 v[122:125], v[164:167], v[190:193], v[122:125]
	v_mfma_f32_16x16x32_bf16 v[118:121], v[174:177], v[190:193], v[118:121]
	v_mfma_f32_16x16x32_bf16 v[118:121], v[178:181], v[194:197], v[118:121]
	v_mfma_f32_16x16x32_bf16 v[114:117], v[186:189], v[194:197], v[114:117]
	v_mfma_f32_16x16x32_bf16 v[114:117], v[182:185], v[190:193], v[114:117]
	v_mfma_f32_16x16x32_bf16 v[98:101], v[182:185], v[198:201], v[98:101]
	v_mfma_f32_16x16x32_bf16 v[98:101], v[186:189], v[202:205], v[98:101]
	v_mfma_f32_16x16x32_bf16 v[102:105], v[178:181], v[202:205], v[102:105]
	v_mfma_f32_16x16x32_bf16 v[102:105], v[174:177], v[198:201], v[102:105]
	v_mfma_f32_16x16x32_bf16 v[106:109], v[164:167], v[198:201], v[106:109]
	v_mfma_f32_16x16x32_bf16 v[106:109], v[168:171], v[202:205], v[106:109]
	v_mfma_f32_16x16x32_bf16 v[110:113], v[160:163], v[202:205], v[110:113]
	v_mfma_f32_16x16x32_bf16 v[110:113], v[156:159], v[198:201], v[110:113]
	v_mfma_f32_16x16x32_bf16 v[94:97], v[156:159], v[206:209], v[94:97]
	v_mfma_f32_16x16x32_bf16 v[94:97], v[160:163], v[210:213], v[94:97]
	v_mfma_f32_16x16x32_bf16 v[90:93], v[168:171], v[210:213], v[90:93]
	v_mfma_f32_16x16x32_bf16 v[90:93], v[164:167], v[206:209], v[90:93]
	v_mfma_f32_16x16x32_bf16 v[86:89], v[174:177], v[206:209], v[86:89]
	v_mfma_f32_16x16x32_bf16 v[86:89], v[178:181], v[210:213], v[86:89]
	v_mfma_f32_16x16x32_bf16 v[82:85], v[186:189], v[210:213], v[82:85]
	v_mfma_f32_16x16x32_bf16 v[82:85], v[182:185], v[206:209], v[82:85]
	v_mfma_f32_16x16x32_bf16 v[66:69], v[182:185], v[214:217], v[66:69]
	v_mfma_f32_16x16x32_bf16 v[66:69], v[186:189], v[218:221], v[66:69]
	v_mfma_f32_16x16x32_bf16 v[70:73], v[178:181], v[218:221], v[70:73]
	v_mfma_f32_16x16x32_bf16 v[70:73], v[174:177], v[214:217], v[70:73]
	v_mfma_f32_16x16x32_bf16 v[74:77], v[164:167], v[214:217], v[74:77]
	v_mfma_f32_16x16x32_bf16 v[74:77], v[168:171], v[218:221], v[74:77]
	v_mfma_f32_16x16x32_bf16 v[78:81], v[160:163], v[218:221], v[78:81]
	v_mfma_f32_16x16x32_bf16 v[78:81], v[156:159], v[214:217], v[78:81]
	v_mfma_f32_16x16x32_bf16 v[62:65], v[156:159], v[222:225], v[62:65]
	v_mfma_f32_16x16x32_bf16 v[62:65], v[160:163], v[226:229], v[62:65]
	v_mfma_f32_16x16x32_bf16 v[58:61], v[168:171], v[226:229], v[58:61]
	v_mfma_f32_16x16x32_bf16 v[58:61], v[164:167], v[222:225], v[58:61]
	v_mfma_f32_16x16x32_bf16 v[54:57], v[174:177], v[222:225], v[54:57]
	v_mfma_f32_16x16x32_bf16 v[54:57], v[178:181], v[226:229], v[54:57]
	v_mfma_f32_16x16x32_bf16 v[50:53], v[186:189], v[226:229], v[50:53]
	v_mfma_f32_16x16x32_bf16 v[50:53], v[182:185], v[222:225], v[50:53]
	v_mfma_f32_16x16x32_bf16 v[34:37], v[182:185], v[230:233], v[34:37]
	v_mfma_f32_16x16x32_bf16 v[34:37], v[186:189], v[234:237], v[34:37]
	v_mfma_f32_16x16x32_bf16 v[38:41], v[178:181], v[234:237], v[38:41]
	v_mfma_f32_16x16x32_bf16 v[38:41], v[174:177], v[230:233], v[38:41]
	v_mfma_f32_16x16x32_bf16 v[42:45], v[164:167], v[230:233], v[42:45]
	v_mfma_f32_16x16x32_bf16 v[42:45], v[168:171], v[234:237], v[42:45]
	v_mfma_f32_16x16x32_bf16 v[46:49], v[160:163], v[234:237], v[46:49]
	v_mfma_f32_16x16x32_bf16 v[46:49], v[156:159], v[230:233], v[46:49]
	v_mfma_f32_16x16x32_bf16 v[30:33], v[156:159], v[238:241], v[30:33]
	v_mfma_f32_16x16x32_bf16 v[30:33], v[160:163], v[242:245], v[30:33]
	v_mfma_f32_16x16x32_bf16 v[26:29], v[168:171], v[242:245], v[26:29]
	v_mfma_f32_16x16x32_bf16 v[26:29], v[164:167], v[238:241], v[26:29]
	v_mfma_f32_16x16x32_bf16 v[22:25], v[174:177], v[238:241], v[22:25]
	v_mfma_f32_16x16x32_bf16 v[22:25], v[178:181], v[242:245], v[22:25]
	v_mfma_f32_16x16x32_bf16 v[18:21], v[186:189], v[242:245], v[18:21]
	v_mfma_f32_16x16x32_bf16 v[18:21], v[182:185], v[238:241], v[18:21]
	v_mfma_f32_16x16x32_bf16 v[2:5], v[182:185], v[246:249], v[2:5]
	v_mfma_f32_16x16x32_bf16 v[2:5], v[186:189], v[250:253], v[2:5]
	v_mfma_f32_16x16x32_bf16 v[6:9], v[178:181], v[250:253], v[6:9]
	v_mfma_f32_16x16x32_bf16 v[6:9], v[174:177], v[246:249], v[6:9]
	v_mfma_f32_16x16x32_bf16 v[10:13], v[164:167], v[246:249], v[10:13]
	v_mfma_f32_16x16x32_bf16 v[10:13], v[168:171], v[250:253], v[10:13]
	v_mfma_f32_16x16x32_bf16 v[14:17], v[160:163], v[250:253], v[14:17]
	v_mfma_f32_16x16x32_bf16 v[14:17], v[156:159], v[246:249], v[14:17]
	s_setprio 0
	s_waitcnt vmcnt(0)
	s_barrier
; #define PG8_STAGE(bufoff, gbase, voff) do { _Pragma("unroll") for (int _i = 0; _i < 2; ++_i) \
;         __builtin_amdgcn_global_load_lds((const unsigned*)((const char*)(gbase) + (voff)[_i]), (PG8_LAS unsigned*)(lds + (bufoff) + ldsw + _i * 8192), 16, 0, 0); } while (0)
; #define PG8_LDA(dst, b, h) do { _Pragma("unroll") for (int m = 0; m < 4; ++m) _Pragma("unroll") for (int k = 0; k < 2; ++k) dst[m][k] = *(const PG8_LAS bf16x8*)(lds + PG8_SA(b, h) + aoff + m * 2048 + k * 1024); } while (0)
; #define PG8_LDB(dst, b, h) do { _Pragma("unroll") for (int n = 0; n < 2; ++n) _Pragma("unroll") for (int k = 0; k < 2; ++k) dst[n][k] = *(const PG8_LAS bf16x8*)(lds + PG8_SB(b, h) + boff + n * 2048 + k * 1024); } while (0)
; #define PG8_WAIT_V(n) asm volatile("s_waitcnt vmcnt(" #n ")" ::: "memory")
; #define PG8_WAIT_L(n) asm volatile("s_waitcnt lgkmcnt(" #n ")" ::: "memory")
; template <class Epi, class Sched, bool ALIGN_EPI>
; __device__ __forceinline__ void gemm_phase(PG8_LAS unsigned char* lds, const Gemm g, const Sched& S, const Epi& E) {
;     ...
;             const char* a1 = cA + (size_t)(t + 1) * kstepA;
;             const char* a2 = last ? nA : cA + (size_t)(t + 2) * kstepA; const char* b2 = last ? nB : cB + (size_t)(t + 2) * kstep;
;             const char* a3 = a2 + kstepA; const char* b3 = b2 + kstep;
;             PG8_LDB(B0, 0, 0); PG8_LDB(B1, 0, 1); PG8_SCHED; PG8_LDA(At, 0, 0); PG8_STAGE(PG8_SA(1, 1), a1 + hstepA, voffA);
;             PG8_WAIT_V(8); PG8_WAIT_L(0); PG8_BAR; PG8_MMA(0, 0, At, B0); PG8_MMA(0, 1, At, B1); PG8_BAR; PG8_SCHED;
;             PG8_LDA(At, 0, 1); PG8_STAGE(PG8_SB(0, 0), b2, voffB); PG8_STAGE(PG8_SB(0, 1), b2 + hstepB, voffB); PG8_STAGE(PG8_SA(0, 0), a2, voffA);
;             PG8_WAIT_V(8); PG8_WAIT_L(0); PG8_BAR; PG8_MMA(1, 0, At, B0); PG8_MMA(1, 1, At, B1); PG8_BAR; PG8_SCHED;
;             PG8_LDB(B0, 1, 0); PG8_LDB(B1, 1, 1); PG8_SCHED; PG8_LDA(At, 1, 0); PG8_STAGE(PG8_SA(0, 1), a2 + hstepA, voffA);
;             PG8_WAIT_V(8); PG8_WAIT_L(0); PG8_BAR; PG8_MMA(0, 0, At, B0); PG8_MMA(0, 1, At, B1); PG8_BAR; PG8_SCHED;
;             PG8_LDA(At, 1, 1); PG8_STAGE(PG8_SB(1, 0), b3, voffB); PG8_STAGE(PG8_SB(1, 1), b3 + hstepB, voffB); PG8_STAGE(PG8_SA(1, 0), a3, voffA);
;             PG8_WAIT_V(8); PG8_WAIT_L(0); PG8_BAR; PG8_MMA(1, 0, At, B0); PG8_MMA(1, 1, At, B1); PG8_BAR; PG8_SCHED;
;         }
	ds_read_b128 v[190:193], v155 offset:32768
	ds_read_b128 v[194:197], v155 offset:33792
	ds_read_b128 v[198:201], v155 offset:34816
	s_cmp_eq_u32 s49, 15
	s_cselect_b32 s28, s50, s28
	s_cselect_b32 s29, s51, s29
	s_add_i32 m0, s2, 0x10000
	s_nop 0
	global_load_lds_dwordx4 v134, s[28:29]
	ds_read_b128 v[202:205], v155 offset:35840
	ds_read_b128 v[206:209], v155 offset:36864
	ds_read_b128 v[210:213], v155 offset:37888
	s_add_i32 m0, s2, 0x12000
	s_nop 0
	global_load_lds_dwordx4 v130, s[28:29]
	ds_read_b128 v[214:217], v155 offset:38912
	ds_read_b128 v[218:221], v155 offset:39936
	ds_read_b128 v[156:159], v153 offset:32768
	s_add_u32 s30, s28, 0x20000
	s_addc_u32 s31, s29, 0
	s_add_i32 m0, s2, 0x11000
	s_nop 0
	global_load_lds_dwordx4 v134, s[30:31]
	ds_read_b128 v[160:163], v153 offset:33792
	ds_read_b128 v[164:167], v153 offset:34816
	ds_read_b128 v[168:171], v153 offset:35840
	s_add_i32 m0, s2, 0x13000
	s_nop 0
	global_load_lds_dwordx4 v130, s[30:31]
	ds_read_b128 v[174:177], v153 offset:49152
	ds_read_b128 v[178:181], v153 offset:50176
	ds_read_b128 v[182:185], v153 offset:51200
	s_add_u32 s30, s28, 0x80000
	s_addc_u32 s31, s29, 0
	s_add_i32 m0, s2, 0x14000
	s_nop 0
	global_load_lds_dwordx4 v134, s[30:31]
	ds_read_b128 v[186:189], v153 offset:52224
	ds_read_b128 v[222:225], v155 offset:49152
	ds_read_b128 v[226:229], v155 offset:50176
	s_add_i32 m0, s2, 0x16000
	s_nop 0
	global_load_lds_dwordx4 v130, s[30:31]
	ds_read_b128 v[230:233], v155 offset:51200
	ds_read_b128 v[234:237], v155 offset:52224
	ds_read_b128 v[238:241], v155 offset:53248
	s_add_u32 s30, s28, 0xa0000
	s_addc_u32 s31, s29, 0
	s_add_i32 m0, s2, 0x15000
	s_nop 0
	global_load_lds_dwordx4 v134, s[30:31]
	ds_read_b128 v[242:245], v155 offset:54272
	ds_read_b128 v[246:249], v155 offset:55296
	ds_read_b128 v[250:253], v155 offset:56320
	s_add_i32 m0, s2, 0x17000
	s_nop 0
	global_load_lds_dwordx4 v130, s[30:31]
	s_add_u32 s28, s28, 0x80
	s_addc_u32 s29, s29, 0
	s_waitcnt vmcnt(8) lgkmcnt(0)
	s_barrier
	s_setprio 1
	v_mfma_f32_16x16x32_bf16 v[126:129], v[156:159], v[190:193], v[126:129]
	v_mfma_f32_16x16x32_bf16 v[126:129], v[160:163], v[194:197], v[126:129]
	v_mfma_f32_16x16x32_bf16 v[122:125], v[168:171], v[194:197], v[122:125]
	v_mfma_f32_16x16x32_bf16 v[122:125], v[164:167], v[190:193], v[122:125]
	v_mfma_f32_16x16x32_bf16 v[118:121], v[174:177], v[190:193], v[118:121]
	v_mfma_f32_16x16x32_bf16 v[118:121], v[178:181], v[194:197], v[118:121]
	v_mfma_f32_16x16x32_bf16 v[114:117], v[186:189], v[194:197], v[114:117]
	v_mfma_f32_16x16x32_bf16 v[114:117], v[182:185], v[190:193], v[114:117]
	v_mfma_f32_16x16x32_bf16 v[98:101], v[182:185], v[198:201], v[98:101]
	v_mfma_f32_16x16x32_bf16 v[98:101], v[186:189], v[202:205], v[98:101]
	v_mfma_f32_16x16x32_bf16 v[102:105], v[178:181], v[202:205], v[102:105]
	v_mfma_f32_16x16x32_bf16 v[102:105], v[174:177], v[198:201], v[102:105]
	v_mfma_f32_16x16x32_bf16 v[106:109], v[164:167], v[198:201], v[106:109]
	v_mfma_f32_16x16x32_bf16 v[106:109], v[168:171], v[202:205], v[106:109]
	v_mfma_f32_16x16x32_bf16 v[110:113], v[160:163], v[202:205], v[110:113]
	v_mfma_f32_16x16x32_bf16 v[110:113], v[156:159], v[198:201], v[110:113]
	v_mfma_f32_16x16x32_bf16 v[94:97], v[156:159], v[206:209], v[94:97]
	v_mfma_f32_16x16x32_bf16 v[94:97], v[160:163], v[210:213], v[94:97]
	v_mfma_f32_16x16x32_bf16 v[90:93], v[168:171], v[210:213], v[90:93]
	v_mfma_f32_16x16x32_bf16 v[90:93], v[164:167], v[206:209], v[90:93]
	v_mfma_f32_16x16x32_bf16 v[86:89], v[174:177], v[206:209], v[86:89]
	v_mfma_f32_16x16x32_bf16 v[86:89], v[178:181], v[210:213], v[86:89]
	v_mfma_f32_16x16x32_bf16 v[82:85], v[186:189], v[210:213], v[82:85]
	v_mfma_f32_16x16x32_bf16 v[82:85], v[182:185], v[206:209], v[82:85]
	v_mfma_f32_16x16x32_bf16 v[66:69], v[182:185], v[214:217], v[66:69]
	v_mfma_f32_16x16x32_bf16 v[66:69], v[186:189], v[218:221], v[66:69]
	v_mfma_f32_16x16x32_bf16 v[70:73], v[178:181], v[218:221], v[70:73]
	v_mfma_f32_16x16x32_bf16 v[70:73], v[174:177], v[214:217], v[70:73]
	v_mfma_f32_16x16x32_bf16 v[74:77], v[164:167], v[214:217], v[74:77]
	v_mfma_f32_16x16x32_bf16 v[74:77], v[168:171], v[218:221], v[74:77]
	v_mfma_f32_16x16x32_bf16 v[78:81], v[160:163], v[218:221], v[78:81]
	v_mfma_f32_16x16x32_bf16 v[78:81], v[156:159], v[214:217], v[78:81]
	v_mfma_f32_16x16x32_bf16 v[62:65], v[156:159], v[222:225], v[62:65]
	v_mfma_f32_16x16x32_bf16 v[62:65], v[160:163], v[226:229], v[62:65]
	v_mfma_f32_16x16x32_bf16 v[58:61], v[168:171], v[226:229], v[58:61]
	v_mfma_f32_16x16x32_bf16 v[58:61], v[164:167], v[222:225], v[58:61]
	v_mfma_f32_16x16x32_bf16 v[54:57], v[174:177], v[222:225], v[54:57]
	v_mfma_f32_16x16x32_bf16 v[54:57], v[178:181], v[226:229], v[54:57]
	v_mfma_f32_16x16x32_bf16 v[50:53], v[186:189], v[226:229], v[50:53]
	v_mfma_f32_16x16x32_bf16 v[50:53], v[182:185], v[222:225], v[50:53]
	v_mfma_f32_16x16x32_bf16 v[34:37], v[182:185], v[230:233], v[34:37]
	v_mfma_f32_16x16x32_bf16 v[34:37], v[186:189], v[234:237], v[34:37]
	v_mfma_f32_16x16x32_bf16 v[38:41], v[178:181], v[234:237], v[38:41]
	v_mfma_f32_16x16x32_bf16 v[38:41], v[174:177], v[230:233], v[38:41]
	v_mfma_f32_16x16x32_bf16 v[42:45], v[164:167], v[230:233], v[42:45]
	v_mfma_f32_16x16x32_bf16 v[42:45], v[168:171], v[234:237], v[42:45]
	v_mfma_f32_16x16x32_bf16 v[46:49], v[160:163], v[234:237], v[46:49]
	v_mfma_f32_16x16x32_bf16 v[46:49], v[156:159], v[230:233], v[46:49]
	v_mfma_f32_16x16x32_bf16 v[30:33], v[156:159], v[238:241], v[30:33]
	v_mfma_f32_16x16x32_bf16 v[30:33], v[160:163], v[242:245], v[30:33]
	v_mfma_f32_16x16x32_bf16 v[26:29], v[168:171], v[242:245], v[26:29]
	v_mfma_f32_16x16x32_bf16 v[26:29], v[164:167], v[238:241], v[26:29]
	v_mfma_f32_16x16x32_bf16 v[22:25], v[174:177], v[238:241], v[22:25]
	v_mfma_f32_16x16x32_bf16 v[22:25], v[178:181], v[242:245], v[22:25]
	v_mfma_f32_16x16x32_bf16 v[18:21], v[186:189], v[242:245], v[18:21]
	v_mfma_f32_16x16x32_bf16 v[18:21], v[182:185], v[238:241], v[18:21]
	v_mfma_f32_16x16x32_bf16 v[2:5], v[182:185], v[246:249], v[2:5]
	v_mfma_f32_16x16x32_bf16 v[2:5], v[186:189], v[250:253], v[2:5]
	v_mfma_f32_16x16x32_bf16 v[6:9], v[178:181], v[250:253], v[6:9]
	v_mfma_f32_16x16x32_bf16 v[6:9], v[174:177], v[246:249], v[6:9]
	v_mfma_f32_16x16x32_bf16 v[10:13], v[164:167], v[246:249], v[10:13]
	v_mfma_f32_16x16x32_bf16 v[10:13], v[168:171], v[250:253], v[10:13]
	v_mfma_f32_16x16x32_bf16 v[14:17], v[160:163], v[250:253], v[14:17]
	v_mfma_f32_16x16x32_bf16 v[14:17], v[156:159], v[246:249], v[14:17]
	s_setprio 0
	s_waitcnt vmcnt(0)
	s_barrier
	s_add_i32 s49, s49, 1
	s_cmp_lt_u32 s49, 16
	s_cbranch_scc1 .Lp8k_A_loop
	s_branch .Lp8k_done

; #define PG8_STAGE(bufoff, gbase, voff) do { _Pragma("unroll") for (int _i = 0; _i < 2; ++_i) \
;         __builtin_amdgcn_global_load_lds((const unsigned*)((const char*)(gbase) + (voff)[_i]), (PG8_LAS unsigned*)(lds + (bufoff) + ldsw + _i * 8192), 16, 0, 0); } while (0)
; #define PG8_LDA(dst, b, h) do { _Pragma("unroll") for (int m = 0; m < 4; ++m) _Pragma("unroll") for (int k = 0; k < 2; ++k) dst[m][k] = *(const PG8_LAS bf16x8*)(lds + PG8_SA(b, h) + aoff + m * 2048 + k * 1024); } while (0)
; #define PG8_LDB(dst, b, h) do { _Pragma("unroll") for (int n = 0; n < 2; ++n) _Pragma("unroll") for (int k = 0; k < 2; ++k) dst[n][k] = *(const PG8_LAS bf16x8*)(lds + PG8_SB(b, h) + boff + n * 2048 + k * 1024); } while (0)
; #define PG8_WAIT_V(n) asm volatile("s_waitcnt vmcnt(" #n ")" ::: "memory")
; #define PG8_WAIT_L(n) asm volatile("s_waitcnt lgkmcnt(" #n ")" ::: "memory")
; template <class Epi, class Sched, bool ALIGN_EPI>
; __device__ __forceinline__ void gemm_phase(PG8_LAS unsigned char* lds, const Gemm g, const Sched& S, const Epi& E) {
;     ...
;             const char* a1 = cA + (size_t)(t + 1) * kstepA;
;             const char* a2 = last ? nA : cA + (size_t)(t + 2) * kstepA; const char* b2 = last ? nB : cB + (size_t)(t + 2) * kstep;
;             const char* a3 = a2 + kstepA; const char* b3 = b2 + kstep;
;             PG8_LDB(B0, 0, 0); PG8_LDB(B1, 0, 1); PG8_SCHED; PG8_LDA(At, 0, 0); PG8_STAGE(PG8_SA(1, 1), a1 + hstepA, voffA);
;             PG8_WAIT_V(8); PG8_WAIT_L(0); PG8_BAR; PG8_MMA(0, 0, At, B0); PG8_MMA(0, 1, At, B1); PG8_BAR; PG8_SCHED;
;             PG8_LDA(At, 0, 1); PG8_STAGE(PG8_SB(0, 0), b2, voffB); PG8_STAGE(PG8_SB(0, 1), b2 + hstepB, voffB); PG8_STAGE(PG8_SA(0, 0), a2, voffA);
;             PG8_WAIT_V(8); PG8_WAIT_L(0); PG8_BAR; PG8_MMA(1, 0, At, B0); PG8_MMA(1, 1, At, B1); PG8_BAR; PG8_SCHED;
;             PG8_LDB(B0, 1, 0); PG8_LDB(B1, 1, 1); PG8_SCHED; PG8_LDA(At, 1, 0); PG8_STAGE(PG8_SA(0, 1), a2 + hstepA, voffA);
;             PG8_WAIT_V(8); PG8_WAIT_L(0); PG8_BAR; PG8_MMA(0, 0, At, B0); PG8_MMA(0, 1, At, B1); PG8_BAR; PG8_SCHED;
;             PG8_LDA(At, 1, 1); PG8_STAGE(PG8_SB(1, 0), b3, voffB); PG8_STAGE(PG8_SB(1, 1), b3 + hstepB, voffB); PG8_STAGE(PG8_SA(1, 0), a3, voffA);
;             PG8_WAIT_V(8); PG8_WAIT_L(0); PG8_BAR; PG8_MMA(1, 0, At, B0); PG8_MMA(1, 1, At, B1); PG8_BAR; PG8_SCHED;
;         }
.Lp8k_B_loop:
	ds_read_b128 v[190:193], v155 offset:0
	ds_read_b128 v[194:197], v155 offset:1024
	ds_read_b128 v[198:201], v155 offset:2048
	s_add_i32 m0, s2, 0xa000
	s_nop 0
	global_load_lds_dwordx4 v132, s[28:29]
	ds_read_b128 v[202:205], v155 offset:3072
	ds_read_b128 v[206:209], v155 offset:4096
	ds_read_b128 v[210:213], v155 offset:5120
	s_add_u32 s30, s28, 0x20000
	s_addc_u32 s31, s29, 0
	s_add_i32 m0, s2, 0xb000
	s_nop 0
	global_load_lds_dwordx4 v132, s[30:31]
	ds_read_b128 v[214:217], v155 offset:6144
	ds_read_b128 v[218:221], v155 offset:7168
	ds_read_b128 v[156:159], v153 offset:0
	s_add_u32 s30, s28, 0x80000
	s_addc_u32 s31, s29, 0
	s_add_i32 m0, s2, 0xe000
	s_nop 0
	global_load_lds_dwordx4 v132, s[30:31]
	ds_read_b128 v[160:163], v153 offset:1024
	ds_read_b128 v[164:167], v153 offset:2048
	ds_read_b128 v[168:171], v153 offset:3072
	s_add_u32 s30, s28, 0xa0000
	s_addc_u32 s31, s29, 0
	s_add_i32 m0, s2, 0xf000
	s_nop 0
	global_load_lds_dwordx4 v132, s[30:31]
	ds_read_b128 v[174:177], v153 offset:16384
	ds_read_b128 v[178:181], v153 offset:17408
	ds_read_b128 v[182:185], v153 offset:18432
	s_add_u32 s34, s28, 0x80
	s_addc_u32 s35, s29, 0
	s_cmp_eq_u32 s49, 15
	s_cselect_b32 s34, s50, s34
	s_cselect_b32 s35, s51, s35
	s_add_i32 m0, s2, 0x0
	s_nop 0
	global_load_lds_dwordx4 v136, s[34:35]
	ds_read_b128 v[186:189], v153 offset:19456
	ds_read_b128 v[222:225], v155 offset:16384
	ds_read_b128 v[226:229], v155 offset:17408
	s_add_u32 s30, s34, 0x20000
	s_addc_u32 s31, s35, 0
	s_add_i32 m0, s2, 0x1000
	s_nop 0
	global_load_lds_dwordx4 v136, s[30:31]
	ds_read_b128 v[230:233], v155 offset:18432
	ds_read_b128 v[234:237], v155 offset:19456
	ds_read_b128 v[238:241], v155 offset:20480
	s_add_u32 s30, s34, 0x80000
	s_addc_u32 s31, s35, 0
	s_add_i32 m0, s2, 0x4000
	s_nop 0
	global_load_lds_dwordx4 v136, s[30:31]
	ds_read_b128 v[242:245], v155 offset:21504
	ds_read_b128 v[246:249], v155 offset:22528
	ds_read_b128 v[250:253], v155 offset:23552
	s_add_u32 s30, s34, 0xa0000
	s_addc_u32 s31, s35, 0
	s_add_i32 m0, s2, 0x5000
	s_nop 0
	global_load_lds_dwordx4 v136, s[30:31]
	s_add_u32 s28, s28, 0x80
	s_addc_u32 s29, s29, 0
	s_waitcnt vmcnt(8) lgkmcnt(0)
	s_barrier
	s_setprio 1
	v_mfma_f32_16x16x32_bf16 v[126:129], v[156:159], v[190:193], v[126:129]
	v_mfma_f32_16x16x32_bf16 v[126:129], v[160:163], v[194:197], v[126:129]
	v_mfma_f32_16x16x32_bf16 v[122:125], v[168:171], v[194:197], v[122:125]
	v_mfma_f32_16x16x32_bf16 v[122:125], v[164:167], v[190:193], v[122:125]
	v_mfma_f32_16x16x32_bf16 v[118:121], v[174:177], v[190:193], v[118:121]
	v_mfma_f32_16x16x32_bf16 v[118:121], v[178:181], v[194:197], v[118:121]
	v_mfma_f32_16x16x32_bf16 v[114:117], v[186:189], v[194:197], v[114:117]
	v_mfma_f32_16x16x32_bf16 v[114:117], v[182:185], v[190:193], v[114:117]
	v_mfma_f32_16x16x32_bf16 v[98:101], v[182:185], v[198:201], v[98:101]
	v_mfma_f32_16x16x32_bf16 v[98:101], v[186:189], v[202:205], v[98:101]
	v_mfma_f32_16x16x32_bf16 v[102:105], v[178:181], v[202:205], v[102:105]
	v_mfma_f32_16x16x32_bf16 v[102:105], v[174:177], v[198:201], v[102:105]
	v_mfma_f32_16x16x32_bf16 v[106:109], v[164:167], v[198:201], v[106:109]
	v_mfma_f32_16x16x32_bf16 v[106:109], v[168:171], v[202:205], v[106:109]
	v_mfma_f32_16x16x32_bf16 v[110:113], v[160:163], v[202:205], v[110:113]
	v_mfma_f32_16x16x32_bf16 v[110:113], v[156:159], v[198:201], v[110:113]
	v_mfma_f32_16x16x32_bf16 v[94:97], v[156:159], v[206:209], v[94:97]
	v_mfma_f32_16x16x32_bf16 v[94:97], v[160:163], v[210:213], v[94:97]
	v_mfma_f32_16x16x32_bf16 v[90:93], v[168:171], v[210:213], v[90:93]
	v_mfma_f32_16x16x32_bf16 v[90:93], v[164:167], v[206:209], v[90:93]
	v_mfma_f32_16x16x32_bf16 v[86:89], v[174:177], v[206:209], v[86:89]
	v_mfma_f32_16x16x32_bf16 v[86:89], v[178:181], v[210:213], v[86:89]
	v_mfma_f32_16x16x32_bf16 v[82:85], v[186:189], v[210:213], v[82:85]
	v_mfma_f32_16x16x32_bf16 v[82:85], v[182:185], v[206:209], v[82:85]
	v_mfma_f32_16x16x32_bf16 v[66:69], v[182:185], v[214:217], v[66:69]
	v_mfma_f32_16x16x32_bf16 v[66:69], v[186:189], v[218:221], v[66:69]
	v_mfma_f32_16x16x32_bf16 v[70:73], v[178:181], v[218:221], v[70:73]
	v_mfma_f32_16x16x32_bf16 v[70:73], v[174:177], v[214:217], v[70:73]
	v_mfma_f32_16x16x32_bf16 v[74:77], v[164:167], v[214:217], v[74:77]
	v_mfma_f32_16x16x32_bf16 v[74:77], v[168:171], v[218:221], v[74:77]
	v_mfma_f32_16x16x32_bf16 v[78:81], v[160:163], v[218:221], v[78:81]
	v_mfma_f32_16x16x32_bf16 v[78:81], v[156:159], v[214:217], v[78:81]
	v_mfma_f32_16x16x32_bf16 v[62:65], v[156:159], v[222:225], v[62:65]
	v_mfma_f32_16x16x32_bf16 v[62:65], v[160:163], v[226:229], v[62:65]
	v_mfma_f32_16x16x32_bf16 v[58:61], v[168:171], v[226:229], v[58:61]
	v_mfma_f32_16x16x32_bf16 v[58:61], v[164:167], v[222:225], v[58:61]
	v_mfma_f32_16x16x32_bf16 v[54:57], v[174:177], v[222:225], v[54:57]
	v_mfma_f32_16x16x32_bf16 v[54:57], v[178:181], v[226:229], v[54:57]
	v_mfma_f32_16x16x32_bf16 v[50:53], v[186:189], v[226:229], v[50:53]
	v_mfma_f32_16x16x32_bf16 v[50:53], v[182:185], v[222:225], v[50:53]
	v_mfma_f32_16x16x32_bf16 v[34:37], v[182:185], v[230:233], v[34:37]
	v_mfma_f32_16x16x32_bf16 v[34:37], v[186:189], v[234:237], v[34:37]
	v_mfma_f32_16x16x32_bf16 v[38:41], v[178:181], v[234:237], v[38:41]
	v_mfma_f32_16x16x32_bf16 v[38:41], v[174:177], v[230:233], v[38:41]
	v_mfma_f32_16x16x32_bf16 v[42:45], v[164:167], v[230:233], v[42:45]
	v_mfma_f32_16x16x32_bf16 v[42:45], v[168:171], v[234:237], v[42:45]
	v_mfma_f32_16x16x32_bf16 v[46:49], v[160:163], v[234:237], v[46:49]
	v_mfma_f32_16x16x32_bf16 v[46:49], v[156:159], v[230:233], v[46:49]
	v_mfma_f32_16x16x32_bf16 v[30:33], v[156:159], v[238:241], v[30:33]
	v_mfma_f32_16x16x32_bf16 v[30:33], v[160:163], v[242:245], v[30:33]
	v_mfma_f32_16x16x32_bf16 v[26:29], v[168:171], v[242:245], v[26:29]
	v_mfma_f32_16x16x32_bf16 v[26:29], v[164:167], v[238:241], v[26:29]
	v_mfma_f32_16x16x32_bf16 v[22:25], v[174:177], v[238:241], v[22:25]
	v_mfma_f32_16x16x32_bf16 v[22:25], v[178:181], v[242:245], v[22:25]
	v_mfma_f32_16x16x32_bf16 v[18:21], v[186:189], v[242:245], v[18:21]
	v_mfma_f32_16x16x32_bf16 v[18:21], v[182:185], v[238:241], v[18:21]
	v_mfma_f32_16x16x32_bf16 v[2:5], v[182:185], v[246:249], v[2:5]
	v_mfma_f32_16x16x32_bf16 v[2:5], v[186:189], v[250:253], v[2:5]
	v_mfma_f32_16x16x32_bf16 v[6:9], v[178:181], v[250:253], v[6:9]
	v_mfma_f32_16x16x32_bf16 v[6:9], v[174:177], v[246:249], v[6:9]
	v_mfma_f32_16x16x32_bf16 v[10:13], v[164:167], v[246:249], v[10:13]
	v_mfma_f32_16x16x32_bf16 v[10:13], v[168:171], v[250:253], v[10:13]
	v_mfma_f32_16x16x32_bf16 v[14:17], v[160:163], v[250:253], v[14:17]
	v_mfma_f32_16x16x32_bf16 v[14:17], v[156:159], v[246:249], v[14:17]
	s_setprio 0
	s_waitcnt vmcnt(0)
	s_barrier
; #define PG8_STAGE(bufoff, gbase, voff) do { _Pragma("unroll") for (int _i = 0; _i < 2; ++_i) \
;         __builtin_amdgcn_global_load_lds((const unsigned*)((const char*)(gbase) + (voff)[_i]), (PG8_LAS unsigned*)(lds + (bufoff) + ldsw + _i * 8192), 16, 0, 0); } while (0)
; #define PG8_LDA(dst, b, h) do { _Pragma("unroll") for (int m = 0; m < 4; ++m) _Pragma("unroll") for (int k = 0; k < 2; ++k) dst[m][k] = *(const PG8_LAS bf16x8*)(lds + PG8_SA(b, h) + aoff + m * 2048 + k * 1024); } while (0)
; #define PG8_LDB(dst, b, h) do { _Pragma("unroll") for (int n = 0; n < 2; ++n) _Pragma("unroll") for (int k = 0; k < 2; ++k) dst[n][k] = *(const PG8_LAS bf16x8*)(lds + PG8_SB(b, h) + boff + n * 2048 + k * 1024); } while (0)
; #define PG8_WAIT_V(n) asm volatile("s_waitcnt vmcnt(" #n ")" ::: "memory")
; #define PG8_WAIT_L(n) asm volatile("s_waitcnt lgkmcnt(" #n ")" ::: "memory")
; template <class Epi, class Sched, bool ALIGN_EPI>
; __device__ __forceinline__ void gemm_phase(PG8_LAS unsigned char* lds, const Gemm g, const Sched& S, const Epi& E) {
;     ...
;             const char* a1 = cA + (size_t)(t + 1) * kstepA;
;             const char* a2 = last ? nA : cA + (size_t)(t + 2) * kstepA; const char* b2 = last ? nB : cB + (size_t)(t + 2) * kstep;
;             const char* a3 = a2 + kstepA; const char* b3 = b2 + kstep;
;             PG8_LDB(B0, 0, 0); PG8_LDB(B1, 0, 1); PG8_SCHED; PG8_LDA(At, 0, 0); PG8_STAGE(PG8_SA(1, 1), a1 + hstepA, voffA);
;             PG8_WAIT_V(8); PG8_WAIT_L(0); PG8_BAR; PG8_MMA(0, 0, At, B0); PG8_MMA(0, 1, At, B1); PG8_BAR; PG8_SCHED;
;             PG8_LDA(At, 0, 1); PG8_STAGE(PG8_SB(0, 0), b2, voffB); PG8_STAGE(PG8_SB(0, 1), b2 + hstepB, voffB); PG8_STAGE(PG8_SA(0, 0), a2, voffA);
;             PG8_WAIT_V(8); PG8_WAIT_L(0); PG8_BAR; PG8_MMA(1, 0, At, B0); PG8_MMA(1, 1, At, B1); PG8_BAR; PG8_SCHED;
;             PG8_LDB(B0, 1, 0); PG8_LDB(B1, 1, 1); PG8_SCHED; PG8_LDA(At, 1, 0); PG8_STAGE(PG8_SA(0, 1), a2 + hstepA, voffA);
;             PG8_WAIT_V(8); PG8_WAIT_L(0); PG8_BAR; PG8_MMA(0, 0, At, B0); PG8_MMA(0, 1, At, B1); PG8_BAR; PG8_SCHED;
;             PG8_LDA(At, 1, 1); PG8_STAGE(PG8_SB(1, 0), b3, voffB); PG8_STAGE(PG8_SB(1, 1), b3 + hstepB, voffB); PG8_STAGE(PG8_SA(1, 0), a3, voffA);
;             PG8_WAIT_V(8); PG8_WAIT_L(0); PG8_BAR; PG8_MMA(1, 0, At, B0); PG8_MMA(1, 1, At, B1); PG8_BAR; PG8_SCHED;
;         }
	ds_read_b128 v[190:193], v155 offset:32768
	ds_read_b128 v[194:197], v155 offset:33792
	ds_read_b128 v[198:201], v155 offset:34816
	s_cmp_eq_u32 s49, 15
	s_cselect_b32 s28, s50, s28
	s_cselect_b32 s29, s51, s29
	s_add_i32 m0, s2, 0x2000
	s_nop 0
	global_load_lds_dwordx4 v132, s[28:29]
	ds_read_b128 v[202:205], v155 offset:35840
	ds_read_b128 v[206:209], v155 offset:36864
	ds_read_b128 v[210:213], v155 offset:37888
	s_add_u32 s30, s28, 0x20000
	s_addc_u32 s31, s29, 0
	s_add_i32 m0, s2, 0x3000
	s_nop 0
	global_load_lds_dwordx4 v132, s[30:31]
	ds_read_b128 v[214:217], v155 offset:38912
	ds_read_b128 v[218:221], v155 offset:39936
	ds_read_b128 v[156:159], v153 offset:32768
	s_add_u32 s30, s28, 0x80000
	s_addc_u32 s31, s29, 0
	s_add_i32 m0, s2, 0x6000
	s_nop 0
	global_load_lds_dwordx4 v132, s[30:31]
	ds_read_b128 v[160:163], v153 offset:33792
	ds_read_b128 v[164:167], v153 offset:34816
	ds_read_b128 v[168:171], v153 offset:35840
	s_add_u32 s30, s28, 0xa0000
	s_addc_u32 s31, s29, 0
	s_add_i32 m0, s2, 0x7000
	s_nop 0
	global_load_lds_dwordx4 v132, s[30:31]
	ds_read_b128 v[174:177], v153 offset:49152
	ds_read_b128 v[178:181], v153 offset:50176
	ds_read_b128 v[182:185], v153 offset:51200
	s_add_u32 s34, s28, 0x80
	s_addc_u32 s35, s29, 0
	s_add_i32 m0, s2, 0x8000
	s_nop 0
	global_load_lds_dwordx4 v136, s[34:35]
	ds_read_b128 v[186:189], v153 offset:52224
	ds_read_b128 v[222:225], v155 offset:49152
	ds_read_b128 v[226:229], v155 offset:50176
	s_add_u32 s30, s34, 0x20000
	s_addc_u32 s31, s35, 0
	s_add_i32 m0, s2, 0x9000
	s_nop 0
	global_load_lds_dwordx4 v136, s[30:31]
	ds_read_b128 v[230:233], v155 offset:51200
	ds_read_b128 v[234:237], v155 offset:52224
	ds_read_b128 v[238:241], v155 offset:53248
	s_add_u32 s30, s34, 0x80000
	s_addc_u32 s31, s35, 0
	s_add_i32 m0, s2, 0xc000
	s_nop 0
	global_load_lds_dwordx4 v136, s[30:31]
	ds_read_b128 v[242:245], v155 offset:54272
	ds_read_b128 v[246:249], v155 offset:55296
	ds_read_b128 v[250:253], v155 offset:56320
	s_add_u32 s30, s34, 0xa0000
	s_addc_u32 s31, s35, 0
	s_add_i32 m0, s2, 0xd000
	s_nop 0
	global_load_lds_dwordx4 v136, s[30:31]
	s_add_u32 s28, s28, 0x80
	s_addc_u32 s29, s29, 0
	s_waitcnt vmcnt(8) lgkmcnt(0)
	s_barrier
	s_setprio 1
	v_mfma_f32_16x16x32_bf16 v[126:129], v[156:159], v[190:193], v[126:129]
	v_mfma_f32_16x16x32_bf16 v[126:129], v[160:163], v[194:197], v[126:129]
	v_mfma_f32_16x16x32_bf16 v[122:125], v[168:171], v[194:197], v[122:125]
	v_mfma_f32_16x16x32_bf16 v[122:125], v[164:167], v[190:193], v[122:125]
	v_mfma_f32_16x16x32_bf16 v[118:121], v[174:177], v[190:193], v[118:121]
	v_mfma_f32_16x16x32_bf16 v[118:121], v[178:181], v[194:197], v[118:121]
	v_mfma_f32_16x16x32_bf16 v[114:117], v[186:189], v[194:197], v[114:117]
	v_mfma_f32_16x16x32_bf16 v[114:117], v[182:185], v[190:193], v[114:117]
	v_mfma_f32_16x16x32_bf16 v[98:101], v[182:185], v[198:201], v[98:101]
	v_mfma_f32_16x16x32_bf16 v[98:101], v[186:189], v[202:205], v[98:101]
	v_mfma_f32_16x16x32_bf16 v[102:105], v[178:181], v[202:205], v[102:105]
	v_mfma_f32_16x16x32_bf16 v[102:105], v[174:177], v[198:201], v[102:105]
	v_mfma_f32_16x16x32_bf16 v[106:109], v[164:167], v[198:201], v[106:109]
	v_mfma_f32_16x16x32_bf16 v[106:109], v[168:171], v[202:205], v[106:109]
	v_mfma_f32_16x16x32_bf16 v[110:113], v[160:163], v[202:205], v[110:113]
	v_mfma_f32_16x16x32_bf16 v[110:113], v[156:159], v[198:201], v[110:113]
	v_mfma_f32_16x16x32_bf16 v[94:97], v[156:159], v[206:209], v[94:97]
	v_mfma_f32_16x16x32_bf16 v[94:97], v[160:163], v[210:213], v[94:97]
	v_mfma_f32_16x16x32_bf16 v[90:93], v[168:171], v[210:213], v[90:93]
	v_mfma_f32_16x16x32_bf16 v[90:93], v[164:167], v[206:209], v[90:93]
	v_mfma_f32_16x16x32_bf16 v[86:89], v[174:177], v[206:209], v[86:89]
	v_mfma_f32_16x16x32_bf16 v[86:89], v[178:181], v[210:213], v[86:89]
	v_mfma_f32_16x16x32_bf16 v[82:85], v[186:189], v[210:213], v[82:85]
	v_mfma_f32_16x16x32_bf16 v[82:85], v[182:185], v[206:209], v[82:85]
	v_mfma_f32_16x16x32_bf16 v[66:69], v[182:185], v[214:217], v[66:69]
	v_mfma_f32_16x16x32_bf16 v[66:69], v[186:189], v[218:221], v[66:69]
	v_mfma_f32_16x16x32_bf16 v[70:73], v[178:181], v[218:221], v[70:73]
	v_mfma_f32_16x16x32_bf16 v[70:73], v[174:177], v[214:217], v[70:73]
	v_mfma_f32_16x16x32_bf16 v[74:77], v[164:167], v[214:217], v[74:77]
	v_mfma_f32_16x16x32_bf16 v[74:77], v[168:171], v[218:221], v[74:77]
	v_mfma_f32_16x16x32_bf16 v[78:81], v[160:163], v[218:221], v[78:81]
	v_mfma_f32_16x16x32_bf16 v[78:81], v[156:159], v[214:217], v[78:81]
	v_mfma_f32_16x16x32_bf16 v[62:65], v[156:159], v[222:225], v[62:65]
	v_mfma_f32_16x16x32_bf16 v[62:65], v[160:163], v[226:229], v[62:65]
	v_mfma_f32_16x16x32_bf16 v[58:61], v[168:171], v[226:229], v[58:61]
	v_mfma_f32_16x16x32_bf16 v[58:61], v[164:167], v[222:225], v[58:61]
	v_mfma_f32_16x16x32_bf16 v[54:57], v[174:177], v[222:225], v[54:57]
	v_mfma_f32_16x16x32_bf16 v[54:57], v[178:181], v[226:229], v[54:57]
	v_mfma_f32_16x16x32_bf16 v[50:53], v[186:189], v[226:229], v[50:53]
	v_mfma_f32_16x16x32_bf16 v[50:53], v[182:185], v[222:225], v[50:53]
	v_mfma_f32_16x16x32_bf16 v[34:37], v[182:185], v[230:233], v[34:37]
	v_mfma_f32_16x16x32_bf16 v[34:37], v[186:189], v[234:237], v[34:37]
	v_mfma_f32_16x16x32_bf16 v[38:41], v[178:181], v[234:237], v[38:41]
	v_mfma_f32_16x16x32_bf16 v[38:41], v[174:177], v[230:233], v[38:41]
	v_mfma_f32_16x16x32_bf16 v[42:45], v[164:167], v[230:233], v[42:45]
	v_mfma_f32_16x16x32_bf16 v[42:45], v[168:171], v[234:237], v[42:45]
	v_mfma_f32_16x16x32_bf16 v[46:49], v[160:163], v[234:237], v[46:49]
	v_mfma_f32_16x16x32_bf16 v[46:49], v[156:159], v[230:233], v[46:49]
	v_mfma_f32_16x16x32_bf16 v[30:33], v[156:159], v[238:241], v[30:33]
	v_mfma_f32_16x16x32_bf16 v[30:33], v[160:163], v[242:245], v[30:33]
	v_mfma_f32_16x16x32_bf16 v[26:29], v[168:171], v[242:245], v[26:29]
	v_mfma_f32_16x16x32_bf16 v[26:29], v[164:167], v[238:241], v[26:29]
	v_mfma_f32_16x16x32_bf16 v[22:25], v[174:177], v[238:241], v[22:25]
	v_mfma_f32_16x16x32_bf16 v[22:25], v[178:181], v[242:245], v[22:25]
	v_mfma_f32_16x16x32_bf16 v[18:21], v[186:189], v[242:245], v[18:21]
	v_mfma_f32_16x16x32_bf16 v[18:21], v[182:185], v[238:241], v[18:21]
	v_mfma_f32_16x16x32_bf16 v[2:5], v[182:185], v[246:249], v[2:5]
	v_mfma_f32_16x16x32_bf16 v[2:5], v[186:189], v[250:253], v[2:5]
	v_mfma_f32_16x16x32_bf16 v[6:9], v[178:181], v[250:253], v[6:9]
	v_mfma_f32_16x16x32_bf16 v[6:9], v[174:177], v[246:249], v[6:9]
	v_mfma_f32_16x16x32_bf16 v[10:13], v[164:167], v[246:249], v[10:13]
	v_mfma_f32_16x16x32_bf16 v[10:13], v[168:171], v[250:253], v[10:13]
	v_mfma_f32_16x16x32_bf16 v[14:17], v[160:163], v[250:253], v[14:17]
	v_mfma_f32_16x16x32_bf16 v[14:17], v[156:159], v[246:249], v[14:17]
	s_setprio 0
	s_waitcnt vmcnt(0)
	s_barrier
	s_add_i32 s49, s49, 1
	s_cmp_lt_u32 s49, 16
	s_cbranch_scc1 .Lp8k_B_loop

; #define PG8_STAGE(bufoff, gbase, voff) do { _Pragma("unroll") for (int _i = 0; _i < 2; ++_i) \
;         __builtin_amdgcn_global_load_lds((const unsigned*)((const char*)(gbase) + (voff)[_i]), (PG8_LAS unsigned*)(lds + (bufoff) + ldsw + _i * 8192), 16, 0, 0); } while (0)
; #define PG8_LDA(dst, b, h) do { _Pragma("unroll") for (int m = 0; m < 4; ++m) _Pragma("unroll") for (int k = 0; k < 2; ++k) dst[m][k] = *(const PG8_LAS bf16x8*)(lds + PG8_SA(b, h) + aoff + m * 2048 + k * 1024); } while (0)
; #define PG8_LDB(dst, b, h) do { _Pragma("unroll") for (int n = 0; n < 2; ++n) _Pragma("unroll") for (int k = 0; k < 2; ++k) dst[n][k] = *(const PG8_LAS bf16x8*)(lds + PG8_SB(b, h) + boff + n * 2048 + k * 1024); } while (0)
; #define PG8_WAIT_V(n) asm volatile("s_waitcnt vmcnt(" #n ")" ::: "memory")
; #define PG8_WAIT_L(n) asm volatile("s_waitcnt lgkmcnt(" #n ")" ::: "memory")
; template <class Epi, class Sched, bool ALIGN_EPI>
; __device__ __forceinline__ void gemm_phase(PG8_LAS unsigned char* lds, const Gemm g, const Sched& S, const Epi& E) {
;     ...
;             const char* a1 = cA + (size_t)(t + 1) * kstepA;
;             const char* a2 = last ? nA : cA + (size_t)(t + 2) * kstepA; const char* b2 = last ? nB : cB + (size_t)(t + 2) * kstep;
;             const char* a3 = a2 + kstepA; const char* b3 = b2 + kstep;
;             PG8_LDB(B0, 0, 0); PG8_LDB(B1, 0, 1); PG8_SCHED; PG8_LDA(At, 0, 0); PG8_STAGE(PG8_SA(1, 1), a1 + hstepA, voffA);
;             PG8_WAIT_V(8); PG8_WAIT_L(0); PG8_BAR; PG8_MMA(0, 0, At, B0); PG8_MMA(0, 1, At, B1); PG8_BAR; PG8_SCHED;
;             PG8_LDA(At, 0, 1); PG8_STAGE(PG8_SB(0, 0), b2, voffB); PG8_STAGE(PG8_SB(0, 1), b2 + hstepB, voffB); PG8_STAGE(PG8_SA(0, 0), a2, voffA);
;             PG8_WAIT_V(8); PG8_WAIT_L(0); PG8_BAR; PG8_MMA(1, 0, At, B0); PG8_MMA(1, 1, At, B1); PG8_BAR; PG8_SCHED;
;             PG8_LDB(B0, 1, 0); PG8_LDB(B1, 1, 1); PG8_SCHED; PG8_LDA(At, 1, 0); PG8_STAGE(PG8_SA(0, 1), a2 + hstepA, voffA);
;             PG8_WAIT_V(8); PG8_WAIT_L(0); PG8_BAR; PG8_MMA(0, 0, At, B0); PG8_MMA(0, 1, At, B1); PG8_BAR; PG8_SCHED;
;             PG8_LDA(At, 1, 1); PG8_STAGE(PG8_SB(1, 0), b3, voffB); PG8_STAGE(PG8_SB(1, 1), b3 + hstepB, voffB); PG8_STAGE(PG8_SA(1, 0), a3, voffA);
;             PG8_WAIT_V(8); PG8_WAIT_L(0); PG8_BAR; PG8_MMA(1, 0, At, B0); PG8_MMA(1, 1, At, B1); PG8_BAR; PG8_SCHED;
;         }
.Lp9k_A_loop:
	ds_read_b128 v[194:197], v157 offset:0
	ds_read_b128 v[198:201], v157 offset:1024
	ds_read_b128 v[202:205], v157 offset:2048
	s_add_i32 m0, s60, 0x18000
	s_nop 0
	global_load_lds_dwordx4 v132, s[28:29]
	ds_read_b128 v[206:209], v157 offset:3072
	ds_read_b128 v[210:213], v157 offset:4096
	ds_read_b128 v[214:217], v157 offset:5120
	s_add_i32 m0, s60, 0x1a000
	s_nop 0
	global_load_lds_dwordx4 v136, s[28:29]
	ds_read_b128 v[218:221], v157 offset:6144
	ds_read_b128 v[222:225], v157 offset:7168
	ds_read_b128 v[158:161], v155 offset:0
	s_add_u32 s30, s28, 0x58000
	s_addc_u32 s31, s29, 0
	s_add_i32 m0, s60, 0x19000
	s_nop 0
	global_load_lds_dwordx4 v132, s[30:31]
	ds_read_b128 v[162:165], v155 offset:1024
	ds_read_b128 v[166:169], v155 offset:2048
	ds_read_b128 v[174:177], v155 offset:3072
	s_add_i32 m0, s60, 0x1b000
	s_nop 0
	global_load_lds_dwordx4 v136, s[30:31]
	ds_read_b128 v[178:181], v155 offset:16384
	ds_read_b128 v[182:185], v155 offset:17408
	ds_read_b128 v[186:189], v155 offset:18432
	s_add_u32 s30, s28, 0x160000
	s_addc_u32 s31, s29, 0
	s_add_i32 m0, s60, 0x1c000
	s_nop 0
	global_load_lds_dwordx4 v132, s[30:31]
	ds_read_b128 v[190:193], v155 offset:19456
	ds_read_b128 v[226:229], v157 offset:16384
	ds_read_b128 v[230:233], v157 offset:17408
	s_add_i32 m0, s60, 0x1e000
	s_nop 0
	global_load_lds_dwordx4 v136, s[30:31]
	ds_read_b128 v[234:237], v157 offset:18432
	ds_read_b128 v[238:241], v157 offset:19456
	ds_read_b128 v[242:245], v157 offset:20480
	s_add_u32 s30, s28, 0x1b8000
	s_addc_u32 s31, s29, 0
	s_add_i32 m0, s60, 0x1d000
	s_nop 0
	global_load_lds_dwordx4 v132, s[30:31]
	ds_read_b128 v[246:249], v157 offset:21504
	ds_read_b128 v[250:253], v157 offset:22528
	ds_read_b128 v[142:145], v157 offset:23552
	s_add_i32 m0, s60, 0x1f000
	s_nop 0
	global_load_lds_dwordx4 v136, s[30:31]
	s_add_u32 s28, s28, 0x80
	s_addc_u32 s29, s29, 0
	s_waitcnt vmcnt(8) lgkmcnt(0)
	s_barrier
	s_setprio 1
	v_mfma_f32_16x16x32_bf16 v[126:129], v[158:161], v[194:197], v[126:129]
	v_mfma_f32_16x16x32_bf16 v[126:129], v[162:165], v[198:201], v[126:129]
	v_mfma_f32_16x16x32_bf16 v[122:125], v[174:177], v[198:201], v[122:125]
	v_mfma_f32_16x16x32_bf16 v[122:125], v[166:169], v[194:197], v[122:125]
	v_mfma_f32_16x16x32_bf16 v[114:117], v[178:181], v[194:197], v[114:117]
	v_mfma_f32_16x16x32_bf16 v[114:117], v[182:185], v[198:201], v[114:117]
	v_mfma_f32_16x16x32_bf16 v[106:109], v[190:193], v[198:201], v[106:109]
	v_mfma_f32_16x16x32_bf16 v[106:109], v[186:189], v[194:197], v[106:109]
	v_mfma_f32_16x16x32_bf16 v[90:93], v[186:189], v[202:205], v[90:93]
	v_mfma_f32_16x16x32_bf16 v[90:93], v[190:193], v[206:209], v[90:93]
	v_mfma_f32_16x16x32_bf16 v[98:101], v[182:185], v[206:209], v[98:101]
	v_mfma_f32_16x16x32_bf16 v[98:101], v[178:181], v[202:205], v[98:101]
	v_mfma_f32_16x16x32_bf16 v[110:113], v[166:169], v[202:205], v[110:113]
	v_mfma_f32_16x16x32_bf16 v[110:113], v[174:177], v[206:209], v[110:113]
	v_mfma_f32_16x16x32_bf16 v[118:121], v[162:165], v[206:209], v[118:121]
	v_mfma_f32_16x16x32_bf16 v[118:121], v[158:161], v[202:205], v[118:121]
	v_mfma_f32_16x16x32_bf16 v[102:105], v[158:161], v[210:213], v[102:105]
	v_mfma_f32_16x16x32_bf16 v[102:105], v[162:165], v[214:217], v[102:105]
	v_mfma_f32_16x16x32_bf16 v[94:97], v[174:177], v[214:217], v[94:97]
	v_mfma_f32_16x16x32_bf16 v[94:97], v[166:169], v[210:213], v[94:97]
	v_mfma_f32_16x16x32_bf16 v[82:85], v[178:181], v[210:213], v[82:85]
	v_mfma_f32_16x16x32_bf16 v[82:85], v[182:185], v[214:217], v[82:85]
	v_mfma_f32_16x16x32_bf16 v[74:77], v[190:193], v[214:217], v[74:77]
	v_mfma_f32_16x16x32_bf16 v[74:77], v[186:189], v[210:213], v[74:77]
	v_mfma_f32_16x16x32_bf16 v[66:69], v[186:189], v[218:221], v[66:69]
	v_mfma_f32_16x16x32_bf16 v[66:69], v[190:193], v[222:225], v[66:69]
	v_mfma_f32_16x16x32_bf16 v[70:73], v[182:185], v[222:225], v[70:73]
	v_mfma_f32_16x16x32_bf16 v[70:73], v[178:181], v[218:221], v[70:73]
	v_mfma_f32_16x16x32_bf16 v[78:81], v[166:169], v[218:221], v[78:81]
	v_mfma_f32_16x16x32_bf16 v[78:81], v[174:177], v[222:225], v[78:81]
	v_mfma_f32_16x16x32_bf16 v[86:89], v[162:165], v[222:225], v[86:89]
	v_mfma_f32_16x16x32_bf16 v[86:89], v[158:161], v[218:221], v[86:89]
	v_mfma_f32_16x16x32_bf16 v[62:65], v[158:161], v[226:229], v[62:65]
	v_mfma_f32_16x16x32_bf16 v[62:65], v[162:165], v[230:233], v[62:65]
	v_mfma_f32_16x16x32_bf16 v[58:61], v[174:177], v[230:233], v[58:61]
	v_mfma_f32_16x16x32_bf16 v[58:61], v[166:169], v[226:229], v[58:61]
	v_mfma_f32_16x16x32_bf16 v[50:53], v[178:181], v[226:229], v[50:53]
	v_mfma_f32_16x16x32_bf16 v[50:53], v[182:185], v[230:233], v[50:53]
	v_mfma_f32_16x16x32_bf16 v[42:45], v[190:193], v[230:233], v[42:45]
	v_mfma_f32_16x16x32_bf16 v[42:45], v[186:189], v[226:229], v[42:45]
	v_mfma_f32_16x16x32_bf16 v[26:29], v[186:189], v[234:237], v[26:29]
	v_mfma_f32_16x16x32_bf16 v[26:29], v[190:193], v[238:241], v[26:29]
	v_mfma_f32_16x16x32_bf16 v[34:37], v[182:185], v[238:241], v[34:37]
	v_mfma_f32_16x16x32_bf16 v[34:37], v[178:181], v[234:237], v[34:37]
	v_mfma_f32_16x16x32_bf16 v[46:49], v[166:169], v[234:237], v[46:49]
	v_mfma_f32_16x16x32_bf16 v[46:49], v[174:177], v[238:241], v[46:49]
	v_mfma_f32_16x16x32_bf16 v[54:57], v[162:165], v[238:241], v[54:57]
	v_mfma_f32_16x16x32_bf16 v[54:57], v[158:161], v[234:237], v[54:57]
	v_mfma_f32_16x16x32_bf16 v[38:41], v[158:161], v[242:245], v[38:41]
	v_mfma_f32_16x16x32_bf16 v[38:41], v[162:165], v[246:249], v[38:41]
	v_mfma_f32_16x16x32_bf16 v[30:33], v[174:177], v[246:249], v[30:33]
	v_mfma_f32_16x16x32_bf16 v[30:33], v[166:169], v[242:245], v[30:33]
	v_mfma_f32_16x16x32_bf16 v[18:21], v[178:181], v[242:245], v[18:21]
	v_mfma_f32_16x16x32_bf16 v[18:21], v[182:185], v[246:249], v[18:21]
	v_mfma_f32_16x16x32_bf16 v[10:13], v[190:193], v[246:249], v[10:13]
	v_mfma_f32_16x16x32_bf16 v[10:13], v[186:189], v[242:245], v[10:13]
	v_mfma_f32_16x16x32_bf16 v[2:5], v[186:189], v[250:253], v[2:5]
	v_mfma_f32_16x16x32_bf16 v[2:5], v[190:193], v[142:145], v[2:5]
	v_mfma_f32_16x16x32_bf16 v[6:9], v[182:185], v[142:145], v[6:9]
	v_mfma_f32_16x16x32_bf16 v[6:9], v[178:181], v[250:253], v[6:9]
	v_mfma_f32_16x16x32_bf16 v[14:17], v[166:169], v[250:253], v[14:17]
	v_mfma_f32_16x16x32_bf16 v[14:17], v[174:177], v[142:145], v[14:17]
	v_mfma_f32_16x16x32_bf16 v[22:25], v[162:165], v[142:145], v[22:25]
	v_mfma_f32_16x16x32_bf16 v[22:25], v[158:161], v[250:253], v[22:25]
	s_setprio 0
	s_waitcnt vmcnt(0)
	s_barrier
; #define PG8_STAGE(bufoff, gbase, voff) do { _Pragma("unroll") for (int _i = 0; _i < 2; ++_i) \
;         __builtin_amdgcn_global_load_lds((const unsigned*)((const char*)(gbase) + (voff)[_i]), (PG8_LAS unsigned*)(lds + (bufoff) + ldsw + _i * 8192), 16, 0, 0); } while (0)
; #define PG8_LDA(dst, b, h) do { _Pragma("unroll") for (int m = 0; m < 4; ++m) _Pragma("unroll") for (int k = 0; k < 2; ++k) dst[m][k] = *(const PG8_LAS bf16x8*)(lds + PG8_SA(b, h) + aoff + m * 2048 + k * 1024); } while (0)
; #define PG8_LDB(dst, b, h) do { _Pragma("unroll") for (int n = 0; n < 2; ++n) _Pragma("unroll") for (int k = 0; k < 2; ++k) dst[n][k] = *(const PG8_LAS bf16x8*)(lds + PG8_SB(b, h) + boff + n * 2048 + k * 1024); } while (0)
; #define PG8_WAIT_V(n) asm volatile("s_waitcnt vmcnt(" #n ")" ::: "memory")
; #define PG8_WAIT_L(n) asm volatile("s_waitcnt lgkmcnt(" #n ")" ::: "memory")
; template <class Epi, class Sched, bool ALIGN_EPI>
; __device__ __forceinline__ void gemm_phase(PG8_LAS unsigned char* lds, const Gemm g, const Sched& S, const Epi& E) {
;     ...
;             const char* a1 = cA + (size_t)(t + 1) * kstepA;
;             const char* a2 = last ? nA : cA + (size_t)(t + 2) * kstepA; const char* b2 = last ? nB : cB + (size_t)(t + 2) * kstep;
;             const char* a3 = a2 + kstepA; const char* b3 = b2 + kstep;
;             PG8_LDB(B0, 0, 0); PG8_LDB(B1, 0, 1); PG8_SCHED; PG8_LDA(At, 0, 0); PG8_STAGE(PG8_SA(1, 1), a1 + hstepA, voffA);
;             PG8_WAIT_V(8); PG8_WAIT_L(0); PG8_BAR; PG8_MMA(0, 0, At, B0); PG8_MMA(0, 1, At, B1); PG8_BAR; PG8_SCHED;
;             PG8_LDA(At, 0, 1); PG8_STAGE(PG8_SB(0, 0), b2, voffB); PG8_STAGE(PG8_SB(0, 1), b2 + hstepB, voffB); PG8_STAGE(PG8_SA(0, 0), a2, voffA);
;             PG8_WAIT_V(8); PG8_WAIT_L(0); PG8_BAR; PG8_MMA(1, 0, At, B0); PG8_MMA(1, 1, At, B1); PG8_BAR; PG8_SCHED;
;             PG8_LDB(B0, 1, 0); PG8_LDB(B1, 1, 1); PG8_SCHED; PG8_LDA(At, 1, 0); PG8_STAGE(PG8_SA(0, 1), a2 + hstepA, voffA);
;             PG8_WAIT_V(8); PG8_WAIT_L(0); PG8_BAR; PG8_MMA(0, 0, At, B0); PG8_MMA(0, 1, At, B1); PG8_BAR; PG8_SCHED;
;             PG8_LDA(At, 1, 1); PG8_STAGE(PG8_SB(1, 0), b3, voffB); PG8_STAGE(PG8_SB(1, 1), b3 + hstepB, voffB); PG8_STAGE(PG8_SA(1, 0), a3, voffA);
;             PG8_WAIT_V(8); PG8_WAIT_L(0); PG8_BAR; PG8_MMA(1, 0, At, B0); PG8_MMA(1, 1, At, B1); PG8_BAR; PG8_SCHED;
;         }
	ds_read_b128 v[194:197], v157 offset:32768
	ds_read_b128 v[198:201], v157 offset:33792
	ds_read_b128 v[202:205], v157 offset:34816
	s_cmp_eq_u32 s57, 43
	s_cselect_b32 s28, s58, s28
	s_cselect_b32 s29, s59, s29
	s_add_i32 m0, s60, 0x10000
	s_nop 0
	global_load_lds_dwordx4 v132, s[28:29]
	ds_read_b128 v[206:209], v157 offset:35840
	ds_read_b128 v[210:213], v157 offset:36864
	ds_read_b128 v[214:217], v157 offset:37888
	s_add_i32 m0, s60, 0x12000
	s_nop 0
	global_load_lds_dwordx4 v136, s[28:29]
	ds_read_b128 v[218:221], v157 offset:38912
	ds_read_b128 v[222:225], v157 offset:39936
	ds_read_b128 v[158:161], v155 offset:32768
	s_add_u32 s30, s28, 0x58000
	s_addc_u32 s31, s29, 0
	s_add_i32 m0, s60, 0x11000
	s_nop 0
	global_load_lds_dwordx4 v132, s[30:31]
	ds_read_b128 v[162:165], v155 offset:33792
	ds_read_b128 v[166:169], v155 offset:34816
	ds_read_b128 v[174:177], v155 offset:35840
	s_add_i32 m0, s60, 0x13000
	s_nop 0
	global_load_lds_dwordx4 v136, s[30:31]
	ds_read_b128 v[178:181], v155 offset:49152
	ds_read_b128 v[182:185], v155 offset:50176
	ds_read_b128 v[186:189], v155 offset:51200
	s_add_u32 s30, s28, 0x160000
	s_addc_u32 s31, s29, 0
	s_add_i32 m0, s60, 0x14000
	s_nop 0
	global_load_lds_dwordx4 v132, s[30:31]
	ds_read_b128 v[190:193], v155 offset:52224
	ds_read_b128 v[226:229], v157 offset:49152
	ds_read_b128 v[230:233], v157 offset:50176
	s_add_i32 m0, s60, 0x16000
	s_nop 0
	global_load_lds_dwordx4 v136, s[30:31]
	ds_read_b128 v[234:237], v157 offset:51200
	ds_read_b128 v[238:241], v157 offset:52224
	ds_read_b128 v[242:245], v157 offset:53248
	s_add_u32 s30, s28, 0x1b8000
	s_addc_u32 s31, s29, 0
	s_add_i32 m0, s60, 0x15000
	s_nop 0
	global_load_lds_dwordx4 v132, s[30:31]
	ds_read_b128 v[246:249], v157 offset:54272
	ds_read_b128 v[250:253], v157 offset:55296
	ds_read_b128 v[142:145], v157 offset:56320
	s_add_i32 m0, s60, 0x17000
	s_nop 0
	global_load_lds_dwordx4 v136, s[30:31]
	s_add_u32 s28, s28, 0x80
	s_addc_u32 s29, s29, 0
	s_waitcnt vmcnt(8) lgkmcnt(0)
	s_barrier
	s_setprio 1
	v_mfma_f32_16x16x32_bf16 v[126:129], v[158:161], v[194:197], v[126:129]
	v_mfma_f32_16x16x32_bf16 v[126:129], v[162:165], v[198:201], v[126:129]
	v_mfma_f32_16x16x32_bf16 v[122:125], v[174:177], v[198:201], v[122:125]
	v_mfma_f32_16x16x32_bf16 v[122:125], v[166:169], v[194:197], v[122:125]
	v_mfma_f32_16x16x32_bf16 v[114:117], v[178:181], v[194:197], v[114:117]
	v_mfma_f32_16x16x32_bf16 v[114:117], v[182:185], v[198:201], v[114:117]
	v_mfma_f32_16x16x32_bf16 v[106:109], v[190:193], v[198:201], v[106:109]
	v_mfma_f32_16x16x32_bf16 v[106:109], v[186:189], v[194:197], v[106:109]
	v_mfma_f32_16x16x32_bf16 v[90:93], v[186:189], v[202:205], v[90:93]
	v_mfma_f32_16x16x32_bf16 v[90:93], v[190:193], v[206:209], v[90:93]
	v_mfma_f32_16x16x32_bf16 v[98:101], v[182:185], v[206:209], v[98:101]
	v_mfma_f32_16x16x32_bf16 v[98:101], v[178:181], v[202:205], v[98:101]
	v_mfma_f32_16x16x32_bf16 v[110:113], v[166:169], v[202:205], v[110:113]
	v_mfma_f32_16x16x32_bf16 v[110:113], v[174:177], v[206:209], v[110:113]
	v_mfma_f32_16x16x32_bf16 v[118:121], v[162:165], v[206:209], v[118:121]
	v_mfma_f32_16x16x32_bf16 v[118:121], v[158:161], v[202:205], v[118:121]
	v_mfma_f32_16x16x32_bf16 v[102:105], v[158:161], v[210:213], v[102:105]
	v_mfma_f32_16x16x32_bf16 v[102:105], v[162:165], v[214:217], v[102:105]
	v_mfma_f32_16x16x32_bf16 v[94:97], v[174:177], v[214:217], v[94:97]
	v_mfma_f32_16x16x32_bf16 v[94:97], v[166:169], v[210:213], v[94:97]
	v_mfma_f32_16x16x32_bf16 v[82:85], v[178:181], v[210:213], v[82:85]
	v_mfma_f32_16x16x32_bf16 v[82:85], v[182:185], v[214:217], v[82:85]
	v_mfma_f32_16x16x32_bf16 v[74:77], v[190:193], v[214:217], v[74:77]
	v_mfma_f32_16x16x32_bf16 v[74:77], v[186:189], v[210:213], v[74:77]
	v_mfma_f32_16x16x32_bf16 v[66:69], v[186:189], v[218:221], v[66:69]
	v_mfma_f32_16x16x32_bf16 v[66:69], v[190:193], v[222:225], v[66:69]
	v_mfma_f32_16x16x32_bf16 v[70:73], v[182:185], v[222:225], v[70:73]
	v_mfma_f32_16x16x32_bf16 v[70:73], v[178:181], v[218:221], v[70:73]
	v_mfma_f32_16x16x32_bf16 v[78:81], v[166:169], v[218:221], v[78:81]
	v_mfma_f32_16x16x32_bf16 v[78:81], v[174:177], v[222:225], v[78:81]
	v_mfma_f32_16x16x32_bf16 v[86:89], v[162:165], v[222:225], v[86:89]
	v_mfma_f32_16x16x32_bf16 v[86:89], v[158:161], v[218:221], v[86:89]
	v_mfma_f32_16x16x32_bf16 v[62:65], v[158:161], v[226:229], v[62:65]
	v_mfma_f32_16x16x32_bf16 v[62:65], v[162:165], v[230:233], v[62:65]
	v_mfma_f32_16x16x32_bf16 v[58:61], v[174:177], v[230:233], v[58:61]
	v_mfma_f32_16x16x32_bf16 v[58:61], v[166:169], v[226:229], v[58:61]
	v_mfma_f32_16x16x32_bf16 v[50:53], v[178:181], v[226:229], v[50:53]
	v_mfma_f32_16x16x32_bf16 v[50:53], v[182:185], v[230:233], v[50:53]
	v_mfma_f32_16x16x32_bf16 v[42:45], v[190:193], v[230:233], v[42:45]
	v_mfma_f32_16x16x32_bf16 v[42:45], v[186:189], v[226:229], v[42:45]
	v_mfma_f32_16x16x32_bf16 v[26:29], v[186:189], v[234:237], v[26:29]
	v_mfma_f32_16x16x32_bf16 v[26:29], v[190:193], v[238:241], v[26:29]
	v_mfma_f32_16x16x32_bf16 v[34:37], v[182:185], v[238:241], v[34:37]
	v_mfma_f32_16x16x32_bf16 v[34:37], v[178:181], v[234:237], v[34:37]
	v_mfma_f32_16x16x32_bf16 v[46:49], v[166:169], v[234:237], v[46:49]
	v_mfma_f32_16x16x32_bf16 v[46:49], v[174:177], v[238:241], v[46:49]
	v_mfma_f32_16x16x32_bf16 v[54:57], v[162:165], v[238:241], v[54:57]
	v_mfma_f32_16x16x32_bf16 v[54:57], v[158:161], v[234:237], v[54:57]
	v_mfma_f32_16x16x32_bf16 v[38:41], v[158:161], v[242:245], v[38:41]
	v_mfma_f32_16x16x32_bf16 v[38:41], v[162:165], v[246:249], v[38:41]
	v_mfma_f32_16x16x32_bf16 v[30:33], v[174:177], v[246:249], v[30:33]
	v_mfma_f32_16x16x32_bf16 v[30:33], v[166:169], v[242:245], v[30:33]
	v_mfma_f32_16x16x32_bf16 v[18:21], v[178:181], v[242:245], v[18:21]
	v_mfma_f32_16x16x32_bf16 v[18:21], v[182:185], v[246:249], v[18:21]
	v_mfma_f32_16x16x32_bf16 v[10:13], v[190:193], v[246:249], v[10:13]
	v_mfma_f32_16x16x32_bf16 v[10:13], v[186:189], v[242:245], v[10:13]
	v_mfma_f32_16x16x32_bf16 v[2:5], v[186:189], v[250:253], v[2:5]
	v_mfma_f32_16x16x32_bf16 v[2:5], v[190:193], v[142:145], v[2:5]
	v_mfma_f32_16x16x32_bf16 v[6:9], v[182:185], v[142:145], v[6:9]
	v_mfma_f32_16x16x32_bf16 v[6:9], v[178:181], v[250:253], v[6:9]
	v_mfma_f32_16x16x32_bf16 v[14:17], v[166:169], v[250:253], v[14:17]
	v_mfma_f32_16x16x32_bf16 v[14:17], v[174:177], v[142:145], v[14:17]
	v_mfma_f32_16x16x32_bf16 v[22:25], v[162:165], v[142:145], v[22:25]
	v_mfma_f32_16x16x32_bf16 v[22:25], v[158:161], v[250:253], v[22:25]
	s_setprio 0
	s_waitcnt vmcnt(0)
	s_barrier
	s_add_i32 s57, s57, 1
	s_cmp_lt_u32 s57, 44
	s_cbranch_scc1 .Lp9k_A_loop
	s_branch .Lp9k_done

; #define PG8_STAGE(bufoff, gbase, voff) do { _Pragma("unroll") for (int _i = 0; _i < 2; ++_i) \
;         __builtin_amdgcn_global_load_lds((const unsigned*)((const char*)(gbase) + (voff)[_i]), (PG8_LAS unsigned*)(lds + (bufoff) + ldsw + _i * 8192), 16, 0, 0); } while (0)
; #define PG8_LDA(dst, b, h) do { _Pragma("unroll") for (int m = 0; m < 4; ++m) _Pragma("unroll") for (int k = 0; k < 2; ++k) dst[m][k] = *(const PG8_LAS bf16x8*)(lds + PG8_SA(b, h) + aoff + m * 2048 + k * 1024); } while (0)
; #define PG8_LDB(dst, b, h) do { _Pragma("unroll") for (int n = 0; n < 2; ++n) _Pragma("unroll") for (int k = 0; k < 2; ++k) dst[n][k] = *(const PG8_LAS bf16x8*)(lds + PG8_SB(b, h) + boff + n * 2048 + k * 1024); } while (0)
; #define PG8_WAIT_V(n) asm volatile("s_waitcnt vmcnt(" #n ")" ::: "memory")
; #define PG8_WAIT_L(n) asm volatile("s_waitcnt lgkmcnt(" #n ")" ::: "memory")
; template <class Epi, class Sched, bool ALIGN_EPI>
; __device__ __forceinline__ void gemm_phase(PG8_LAS unsigned char* lds, const Gemm g, const Sched& S, const Epi& E) {
;     ...
;             const char* a1 = cA + (size_t)(t + 1) * kstepA;
;             const char* a2 = last ? nA : cA + (size_t)(t + 2) * kstepA; const char* b2 = last ? nB : cB + (size_t)(t + 2) * kstep;
;             const char* a3 = a2 + kstepA; const char* b3 = b2 + kstep;
;             PG8_LDB(B0, 0, 0); PG8_LDB(B1, 0, 1); PG8_SCHED; PG8_LDA(At, 0, 0); PG8_STAGE(PG8_SA(1, 1), a1 + hstepA, voffA);
;             PG8_WAIT_V(8); PG8_WAIT_L(0); PG8_BAR; PG8_MMA(0, 0, At, B0); PG8_MMA(0, 1, At, B1); PG8_BAR; PG8_SCHED;
;             PG8_LDA(At, 0, 1); PG8_STAGE(PG8_SB(0, 0), b2, voffB); PG8_STAGE(PG8_SB(0, 1), b2 + hstepB, voffB); PG8_STAGE(PG8_SA(0, 0), a2, voffA);
;             PG8_WAIT_V(8); PG8_WAIT_L(0); PG8_BAR; PG8_MMA(1, 0, At, B0); PG8_MMA(1, 1, At, B1); PG8_BAR; PG8_SCHED;
;             PG8_LDB(B0, 1, 0); PG8_LDB(B1, 1, 1); PG8_SCHED; PG8_LDA(At, 1, 0); PG8_STAGE(PG8_SA(0, 1), a2 + hstepA, voffA);
;             PG8_WAIT_V(8); PG8_WAIT_L(0); PG8_BAR; PG8_MMA(0, 0, At, B0); PG8_MMA(0, 1, At, B1); PG8_BAR; PG8_SCHED;
;             PG8_LDA(At, 1, 1); PG8_STAGE(PG8_SB(1, 0), b3, voffB); PG8_STAGE(PG8_SB(1, 1), b3 + hstepB, voffB); PG8_STAGE(PG8_SA(1, 0), a3, voffA);
;             PG8_WAIT_V(8); PG8_WAIT_L(0); PG8_BAR; PG8_MMA(1, 0, At, B0); PG8_MMA(1, 1, At, B1); PG8_BAR; PG8_SCHED;
;         }
.Lp9k_B_loop:
	ds_read_b128 v[194:197], v157 offset:0
	ds_read_b128 v[198:201], v157 offset:1024
	ds_read_b128 v[202:205], v157 offset:2048
	s_add_i32 m0, s60, 0xa000
	s_nop 0
	global_load_lds_dwordx4 v134, s[28:29]
	ds_read_b128 v[206:209], v157 offset:3072
	ds_read_b128 v[210:213], v157 offset:4096
	ds_read_b128 v[214:217], v157 offset:5120
	s_add_u32 s30, s28, 0x58000
	s_addc_u32 s31, s29, 0
	s_add_i32 m0, s60, 0xb000
	s_nop 0
	global_load_lds_dwordx4 v134, s[30:31]
	ds_read_b128 v[218:221], v157 offset:6144
	ds_read_b128 v[222:225], v157 offset:7168
	ds_read_b128 v[158:161], v155 offset:0
	s_add_u32 s30, s28, 0x160000
	s_addc_u32 s31, s29, 0
	s_add_i32 m0, s60, 0xe000
	s_nop 0
	global_load_lds_dwordx4 v134, s[30:31]
	ds_read_b128 v[162:165], v155 offset:1024
	ds_read_b128 v[166:169], v155 offset:2048
	ds_read_b128 v[174:177], v155 offset:3072
	s_add_u32 s30, s28, 0x1b8000
	s_addc_u32 s31, s29, 0
	s_add_i32 m0, s60, 0xf000
	s_nop 0
	global_load_lds_dwordx4 v134, s[30:31]
	ds_read_b128 v[178:181], v155 offset:16384
	ds_read_b128 v[182:185], v155 offset:17408
	ds_read_b128 v[186:189], v155 offset:18432
	s_add_u32 s34, s28, 0x80
	s_addc_u32 s35, s29, 0
	s_cmp_eq_u32 s57, 43
	s_cselect_b32 s34, s58, s34
	s_cselect_b32 s35, s59, s35
	s_add_i32 m0, s60, 0x0
	s_nop 0
	global_load_lds_dwordx4 v130, s[34:35]
	ds_read_b128 v[190:193], v155 offset:19456
	ds_read_b128 v[226:229], v157 offset:16384
	ds_read_b128 v[230:233], v157 offset:17408
	s_add_u32 s30, s34, 0x58000
	s_addc_u32 s31, s35, 0
	s_add_i32 m0, s60, 0x1000
	s_nop 0
	global_load_lds_dwordx4 v130, s[30:31]
	ds_read_b128 v[234:237], v157 offset:18432
	ds_read_b128 v[238:241], v157 offset:19456
	ds_read_b128 v[242:245], v157 offset:20480
	s_add_u32 s30, s34, 0x160000
	s_addc_u32 s31, s35, 0
	s_add_i32 m0, s60, 0x4000
	s_nop 0
	global_load_lds_dwordx4 v130, s[30:31]
	ds_read_b128 v[246:249], v157 offset:21504
	ds_read_b128 v[250:253], v157 offset:22528
	ds_read_b128 v[142:145], v157 offset:23552
	s_add_u32 s30, s34, 0x1b8000
	s_addc_u32 s31, s35, 0
	s_add_i32 m0, s60, 0x5000
	s_nop 0
	global_load_lds_dwordx4 v130, s[30:31]
	s_add_u32 s28, s28, 0x80
	s_addc_u32 s29, s29, 0
	s_waitcnt vmcnt(8) lgkmcnt(0)
	s_barrier
	s_setprio 1
	v_mfma_f32_16x16x32_bf16 v[126:129], v[158:161], v[194:197], v[126:129]
	v_mfma_f32_16x16x32_bf16 v[126:129], v[162:165], v[198:201], v[126:129]
	v_mfma_f32_16x16x32_bf16 v[122:125], v[174:177], v[198:201], v[122:125]
	v_mfma_f32_16x16x32_bf16 v[122:125], v[166:169], v[194:197], v[122:125]
	v_mfma_f32_16x16x32_bf16 v[114:117], v[178:181], v[194:197], v[114:117]
	v_mfma_f32_16x16x32_bf16 v[114:117], v[182:185], v[198:201], v[114:117]
	v_mfma_f32_16x16x32_bf16 v[106:109], v[190:193], v[198:201], v[106:109]
	v_mfma_f32_16x16x32_bf16 v[106:109], v[186:189], v[194:197], v[106:109]
	v_mfma_f32_16x16x32_bf16 v[90:93], v[186:189], v[202:205], v[90:93]
	v_mfma_f32_16x16x32_bf16 v[90:93], v[190:193], v[206:209], v[90:93]
	v_mfma_f32_16x16x32_bf16 v[98:101], v[182:185], v[206:209], v[98:101]
	v_mfma_f32_16x16x32_bf16 v[98:101], v[178:181], v[202:205], v[98:101]
	v_mfma_f32_16x16x32_bf16 v[110:113], v[166:169], v[202:205], v[110:113]
	v_mfma_f32_16x16x32_bf16 v[110:113], v[174:177], v[206:209], v[110:113]
	v_mfma_f32_16x16x32_bf16 v[118:121], v[162:165], v[206:209], v[118:121]
	v_mfma_f32_16x16x32_bf16 v[118:121], v[158:161], v[202:205], v[118:121]
	v_mfma_f32_16x16x32_bf16 v[102:105], v[158:161], v[210:213], v[102:105]
	v_mfma_f32_16x16x32_bf16 v[102:105], v[162:165], v[214:217], v[102:105]
	v_mfma_f32_16x16x32_bf16 v[94:97], v[174:177], v[214:217], v[94:97]
	v_mfma_f32_16x16x32_bf16 v[94:97], v[166:169], v[210:213], v[94:97]
	v_mfma_f32_16x16x32_bf16 v[82:85], v[178:181], v[210:213], v[82:85]
	v_mfma_f32_16x16x32_bf16 v[82:85], v[182:185], v[214:217], v[82:85]
	v_mfma_f32_16x16x32_bf16 v[74:77], v[190:193], v[214:217], v[74:77]
	v_mfma_f32_16x16x32_bf16 v[74:77], v[186:189], v[210:213], v[74:77]
	v_mfma_f32_16x16x32_bf16 v[66:69], v[186:189], v[218:221], v[66:69]
	v_mfma_f32_16x16x32_bf16 v[66:69], v[190:193], v[222:225], v[66:69]
	v_mfma_f32_16x16x32_bf16 v[70:73], v[182:185], v[222:225], v[70:73]
	v_mfma_f32_16x16x32_bf16 v[70:73], v[178:181], v[218:221], v[70:73]
	v_mfma_f32_16x16x32_bf16 v[78:81], v[166:169], v[218:221], v[78:81]
	v_mfma_f32_16x16x32_bf16 v[78:81], v[174:177], v[222:225], v[78:81]
	v_mfma_f32_16x16x32_bf16 v[86:89], v[162:165], v[222:225], v[86:89]
	v_mfma_f32_16x16x32_bf16 v[86:89], v[158:161], v[218:221], v[86:89]
	v_mfma_f32_16x16x32_bf16 v[62:65], v[158:161], v[226:229], v[62:65]
	v_mfma_f32_16x16x32_bf16 v[62:65], v[162:165], v[230:233], v[62:65]
	v_mfma_f32_16x16x32_bf16 v[58:61], v[174:177], v[230:233], v[58:61]
	v_mfma_f32_16x16x32_bf16 v[58:61], v[166:169], v[226:229], v[58:61]
	v_mfma_f32_16x16x32_bf16 v[50:53], v[178:181], v[226:229], v[50:53]
	v_mfma_f32_16x16x32_bf16 v[50:53], v[182:185], v[230:233], v[50:53]
	v_mfma_f32_16x16x32_bf16 v[42:45], v[190:193], v[230:233], v[42:45]
	v_mfma_f32_16x16x32_bf16 v[42:45], v[186:189], v[226:229], v[42:45]
	v_mfma_f32_16x16x32_bf16 v[26:29], v[186:189], v[234:237], v[26:29]
	v_mfma_f32_16x16x32_bf16 v[26:29], v[190:193], v[238:241], v[26:29]
	v_mfma_f32_16x16x32_bf16 v[34:37], v[182:185], v[238:241], v[34:37]
	v_mfma_f32_16x16x32_bf16 v[34:37], v[178:181], v[234:237], v[34:37]
	v_mfma_f32_16x16x32_bf16 v[46:49], v[166:169], v[234:237], v[46:49]
	v_mfma_f32_16x16x32_bf16 v[46:49], v[174:177], v[238:241], v[46:49]
	v_mfma_f32_16x16x32_bf16 v[54:57], v[162:165], v[238:241], v[54:57]
	v_mfma_f32_16x16x32_bf16 v[54:57], v[158:161], v[234:237], v[54:57]
	v_mfma_f32_16x16x32_bf16 v[38:41], v[158:161], v[242:245], v[38:41]
	v_mfma_f32_16x16x32_bf16 v[38:41], v[162:165], v[246:249], v[38:41]
	v_mfma_f32_16x16x32_bf16 v[30:33], v[174:177], v[246:249], v[30:33]
	v_mfma_f32_16x16x32_bf16 v[30:33], v[166:169], v[242:245], v[30:33]
	v_mfma_f32_16x16x32_bf16 v[18:21], v[178:181], v[242:245], v[18:21]
	v_mfma_f32_16x16x32_bf16 v[18:21], v[182:185], v[246:249], v[18:21]
	v_mfma_f32_16x16x32_bf16 v[10:13], v[190:193], v[246:249], v[10:13]
	v_mfma_f32_16x16x32_bf16 v[10:13], v[186:189], v[242:245], v[10:13]
	v_mfma_f32_16x16x32_bf16 v[2:5], v[186:189], v[250:253], v[2:5]
	v_mfma_f32_16x16x32_bf16 v[2:5], v[190:193], v[142:145], v[2:5]
	v_mfma_f32_16x16x32_bf16 v[6:9], v[182:185], v[142:145], v[6:9]
	v_mfma_f32_16x16x32_bf16 v[6:9], v[178:181], v[250:253], v[6:9]
	v_mfma_f32_16x16x32_bf16 v[14:17], v[166:169], v[250:253], v[14:17]
	v_mfma_f32_16x16x32_bf16 v[14:17], v[174:177], v[142:145], v[14:17]
	v_mfma_f32_16x16x32_bf16 v[22:25], v[162:165], v[142:145], v[22:25]
	v_mfma_f32_16x16x32_bf16 v[22:25], v[158:161], v[250:253], v[22:25]
	s_setprio 0
	s_waitcnt vmcnt(0)
	s_barrier
; #define PG8_STAGE(bufoff, gbase, voff) do { _Pragma("unroll") for (int _i = 0; _i < 2; ++_i) \
;         __builtin_amdgcn_global_load_lds((const unsigned*)((const char*)(gbase) + (voff)[_i]), (PG8_LAS unsigned*)(lds + (bufoff) + ldsw + _i * 8192), 16, 0, 0); } while (0)
; #define PG8_LDA(dst, b, h) do { _Pragma("unroll") for (int m = 0; m < 4; ++m) _Pragma("unroll") for (int k = 0; k < 2; ++k) dst[m][k] = *(const PG8_LAS bf16x8*)(lds + PG8_SA(b, h) + aoff + m * 2048 + k * 1024); } while (0)
; #define PG8_LDB(dst, b, h) do { _Pragma("unroll") for (int n = 0; n < 2; ++n) _Pragma("unroll") for (int k = 0; k < 2; ++k) dst[n][k] = *(const PG8_LAS bf16x8*)(lds + PG8_SB(b, h) + boff + n * 2048 + k * 1024); } while (0)
; #define PG8_WAIT_V(n) asm volatile("s_waitcnt vmcnt(" #n ")" ::: "memory")
; #define PG8_WAIT_L(n) asm volatile("s_waitcnt lgkmcnt(" #n ")" ::: "memory")
; template <class Epi, class Sched, bool ALIGN_EPI>
; __device__ __forceinline__ void gemm_phase(PG8_LAS unsigned char* lds, const Gemm g, const Sched& S, const Epi& E) {
;     ...
;             const char* a1 = cA + (size_t)(t + 1) * kstepA;
;             const char* a2 = last ? nA : cA + (size_t)(t + 2) * kstepA; const char* b2 = last ? nB : cB + (size_t)(t + 2) * kstep;
;             const char* a3 = a2 + kstepA; const char* b3 = b2 + kstep;
;             PG8_LDB(B0, 0, 0); PG8_LDB(B1, 0, 1); PG8_SCHED; PG8_LDA(At, 0, 0); PG8_STAGE(PG8_SA(1, 1), a1 + hstepA, voffA);
;             PG8_WAIT_V(8); PG8_WAIT_L(0); PG8_BAR; PG8_MMA(0, 0, At, B0); PG8_MMA(0, 1, At, B1); PG8_BAR; PG8_SCHED;
;             PG8_LDA(At, 0, 1); PG8_STAGE(PG8_SB(0, 0), b2, voffB); PG8_STAGE(PG8_SB(0, 1), b2 + hstepB, voffB); PG8_STAGE(PG8_SA(0, 0), a2, voffA);
;             PG8_WAIT_V(8); PG8_WAIT_L(0); PG8_BAR; PG8_MMA(1, 0, At, B0); PG8_MMA(1, 1, At, B1); PG8_BAR; PG8_SCHED;
;             PG8_LDB(B0, 1, 0); PG8_LDB(B1, 1, 1); PG8_SCHED; PG8_LDA(At, 1, 0); PG8_STAGE(PG8_SA(0, 1), a2 + hstepA, voffA);
;             PG8_WAIT_V(8); PG8_WAIT_L(0); PG8_BAR; PG8_MMA(0, 0, At, B0); PG8_MMA(0, 1, At, B1); PG8_BAR; PG8_SCHED;
;             PG8_LDA(At, 1, 1); PG8_STAGE(PG8_SB(1, 0), b3, voffB); PG8_STAGE(PG8_SB(1, 1), b3 + hstepB, voffB); PG8_STAGE(PG8_SA(1, 0), a3, voffA);
;             PG8_WAIT_V(8); PG8_WAIT_L(0); PG8_BAR; PG8_MMA(1, 0, At, B0); PG8_MMA(1, 1, At, B1); PG8_BAR; PG8_SCHED;
;         }
	ds_read_b128 v[194:197], v157 offset:32768
	ds_read_b128 v[198:201], v157 offset:33792
	ds_read_b128 v[202:205], v157 offset:34816
	s_cmp_eq_u32 s57, 43
	s_cselect_b32 s28, s58, s28
	s_cselect_b32 s29, s59, s29
	s_add_i32 m0, s60, 0x2000
	s_nop 0
	global_load_lds_dwordx4 v134, s[28:29]
	ds_read_b128 v[206:209], v157 offset:35840
	ds_read_b128 v[210:213], v157 offset:36864
	ds_read_b128 v[214:217], v157 offset:37888
	s_add_u32 s30, s28, 0x58000
	s_addc_u32 s31, s29, 0
	s_add_i32 m0, s60, 0x3000
	s_nop 0
	global_load_lds_dwordx4 v134, s[30:31]
	ds_read_b128 v[218:221], v157 offset:38912
	ds_read_b128 v[222:225], v157 offset:39936
	ds_read_b128 v[158:161], v155 offset:32768
	s_add_u32 s30, s28, 0x160000
	s_addc_u32 s31, s29, 0
	s_add_i32 m0, s60, 0x6000
	s_nop 0
	global_load_lds_dwordx4 v134, s[30:31]
	ds_read_b128 v[162:165], v155 offset:33792
	ds_read_b128 v[166:169], v155 offset:34816
	ds_read_b128 v[174:177], v155 offset:35840
	s_add_u32 s30, s28, 0x1b8000
	s_addc_u32 s31, s29, 0
	s_add_i32 m0, s60, 0x7000
	s_nop 0
	global_load_lds_dwordx4 v134, s[30:31]
	ds_read_b128 v[178:181], v155 offset:49152
	ds_read_b128 v[182:185], v155 offset:50176
	ds_read_b128 v[186:189], v155 offset:51200
	s_add_u32 s34, s28, 0x80
	s_addc_u32 s35, s29, 0
	s_add_i32 m0, s60, 0x8000
	s_nop 0
	global_load_lds_dwordx4 v130, s[34:35]
	ds_read_b128 v[190:193], v155 offset:52224
	ds_read_b128 v[226:229], v157 offset:49152
	ds_read_b128 v[230:233], v157 offset:50176
	s_add_u32 s30, s34, 0x58000
	s_addc_u32 s31, s35, 0
	s_add_i32 m0, s60, 0x9000
	s_nop 0
	global_load_lds_dwordx4 v130, s[30:31]
	ds_read_b128 v[234:237], v157 offset:51200
	ds_read_b128 v[238:241], v157 offset:52224
	ds_read_b128 v[242:245], v157 offset:53248
	s_add_u32 s30, s34, 0x160000
	s_addc_u32 s31, s35, 0
	s_add_i32 m0, s60, 0xc000
	s_nop 0
	global_load_lds_dwordx4 v130, s[30:31]
	ds_read_b128 v[246:249], v157 offset:54272
	ds_read_b128 v[250:253], v157 offset:55296
	ds_read_b128 v[142:145], v157 offset:56320
	s_add_u32 s30, s34, 0x1b8000
	s_addc_u32 s31, s35, 0
	s_add_i32 m0, s60, 0xd000
	s_nop 0
	global_load_lds_dwordx4 v130, s[30:31]
	s_add_u32 s28, s28, 0x80
	s_addc_u32 s29, s29, 0
	s_waitcnt vmcnt(8) lgkmcnt(0)
	s_barrier
	s_setprio 1
	v_mfma_f32_16x16x32_bf16 v[126:129], v[158:161], v[194:197], v[126:129]
	v_mfma_f32_16x16x32_bf16 v[126:129], v[162:165], v[198:201], v[126:129]
	v_mfma_f32_16x16x32_bf16 v[122:125], v[174:177], v[198:201], v[122:125]
	v_mfma_f32_16x16x32_bf16 v[122:125], v[166:169], v[194:197], v[122:125]
	v_mfma_f32_16x16x32_bf16 v[114:117], v[178:181], v[194:197], v[114:117]
	v_mfma_f32_16x16x32_bf16 v[114:117], v[182:185], v[198:201], v[114:117]
	v_mfma_f32_16x16x32_bf16 v[106:109], v[190:193], v[198:201], v[106:109]
	v_mfma_f32_16x16x32_bf16 v[106:109], v[186:189], v[194:197], v[106:109]
	v_mfma_f32_16x16x32_bf16 v[90:93], v[186:189], v[202:205], v[90:93]
	v_mfma_f32_16x16x32_bf16 v[90:93], v[190:193], v[206:209], v[90:93]
	v_mfma_f32_16x16x32_bf16 v[98:101], v[182:185], v[206:209], v[98:101]
	v_mfma_f32_16x16x32_bf16 v[98:101], v[178:181], v[202:205], v[98:101]
	v_mfma_f32_16x16x32_bf16 v[110:113], v[166:169], v[202:205], v[110:113]
	v_mfma_f32_16x16x32_bf16 v[110:113], v[174:177], v[206:209], v[110:113]
	v_mfma_f32_16x16x32_bf16 v[118:121], v[162:165], v[206:209], v[118:121]
	v_mfma_f32_16x16x32_bf16 v[118:121], v[158:161], v[202:205], v[118:121]
	v_mfma_f32_16x16x32_bf16 v[102:105], v[158:161], v[210:213], v[102:105]
	v_mfma_f32_16x16x32_bf16 v[102:105], v[162:165], v[214:217], v[102:105]
	v_mfma_f32_16x16x32_bf16 v[94:97], v[174:177], v[214:217], v[94:97]
	v_mfma_f32_16x16x32_bf16 v[94:97], v[166:169], v[210:213], v[94:97]
	v_mfma_f32_16x16x32_bf16 v[82:85], v[178:181], v[210:213], v[82:85]
	v_mfma_f32_16x16x32_bf16 v[82:85], v[182:185], v[214:217], v[82:85]
	v_mfma_f32_16x16x32_bf16 v[74:77], v[190:193], v[214:217], v[74:77]
	v_mfma_f32_16x16x32_bf16 v[74:77], v[186:189], v[210:213], v[74:77]
	v_mfma_f32_16x16x32_bf16 v[66:69], v[186:189], v[218:221], v[66:69]
	v_mfma_f32_16x16x32_bf16 v[66:69], v[190:193], v[222:225], v[66:69]
	v_mfma_f32_16x16x32_bf16 v[70:73], v[182:185], v[222:225], v[70:73]
	v_mfma_f32_16x16x32_bf16 v[70:73], v[178:181], v[218:221], v[70:73]
	v_mfma_f32_16x16x32_bf16 v[78:81], v[166:169], v[218:221], v[78:81]
	v_mfma_f32_16x16x32_bf16 v[78:81], v[174:177], v[222:225], v[78:81]
	v_mfma_f32_16x16x32_bf16 v[86:89], v[162:165], v[222:225], v[86:89]
	v_mfma_f32_16x16x32_bf16 v[86:89], v[158:161], v[218:221], v[86:89]
	v_mfma_f32_16x16x32_bf16 v[62:65], v[158:161], v[226:229], v[62:65]
	v_mfma_f32_16x16x32_bf16 v[62:65], v[162:165], v[230:233], v[62:65]
	v_mfma_f32_16x16x32_bf16 v[58:61], v[174:177], v[230:233], v[58:61]
	v_mfma_f32_16x16x32_bf16 v[58:61], v[166:169], v[226:229], v[58:61]
	v_mfma_f32_16x16x32_bf16 v[50:53], v[178:181], v[226:229], v[50:53]
	v_mfma_f32_16x16x32_bf16 v[50:53], v[182:185], v[230:233], v[50:53]
	v_mfma_f32_16x16x32_bf16 v[42:45], v[190:193], v[230:233], v[42:45]
	v_mfma_f32_16x16x32_bf16 v[42:45], v[186:189], v[226:229], v[42:45]
	v_mfma_f32_16x16x32_bf16 v[26:29], v[186:189], v[234:237], v[26:29]
	v_mfma_f32_16x16x32_bf16 v[26:29], v[190:193], v[238:241], v[26:29]
	v_mfma_f32_16x16x32_bf16 v[34:37], v[182:185], v[238:241], v[34:37]
	v_mfma_f32_16x16x32_bf16 v[34:37], v[178:181], v[234:237], v[34:37]
	v_mfma_f32_16x16x32_bf16 v[46:49], v[166:169], v[234:237], v[46:49]
	v_mfma_f32_16x16x32_bf16 v[46:49], v[174:177], v[238:241], v[46:49]
	v_mfma_f32_16x16x32_bf16 v[54:57], v[162:165], v[238:241], v[54:57]
	v_mfma_f32_16x16x32_bf16 v[54:57], v[158:161], v[234:237], v[54:57]
	v_mfma_f32_16x16x32_bf16 v[38:41], v[158:161], v[242:245], v[38:41]
	v_mfma_f32_16x16x32_bf16 v[38:41], v[162:165], v[246:249], v[38:41]
	v_mfma_f32_16x16x32_bf16 v[30:33], v[174:177], v[246:249], v[30:33]
	v_mfma_f32_16x16x32_bf16 v[30:33], v[166:169], v[242:245], v[30:33]
	v_mfma_f32_16x16x32_bf16 v[18:21], v[178:181], v[242:245], v[18:21]
	v_mfma_f32_16x16x32_bf16 v[18:21], v[182:185], v[246:249], v[18:21]
	v_mfma_f32_16x16x32_bf16 v[10:13], v[190:193], v[246:249], v[10:13]
	v_mfma_f32_16x16x32_bf16 v[10:13], v[186:189], v[242:245], v[10:13]
	v_mfma_f32_16x16x32_bf16 v[2:5], v[186:189], v[250:253], v[2:5]
	v_mfma_f32_16x16x32_bf16 v[2:5], v[190:193], v[142:145], v[2:5]
	v_mfma_f32_16x16x32_bf16 v[6:9], v[182:185], v[142:145], v[6:9]
	v_mfma_f32_16x16x32_bf16 v[6:9], v[178:181], v[250:253], v[6:9]
	v_mfma_f32_16x16x32_bf16 v[14:17], v[166:169], v[250:253], v[14:17]
	v_mfma_f32_16x16x32_bf16 v[14:17], v[174:177], v[142:145], v[14:17]
	v_mfma_f32_16x16x32_bf16 v[22:25], v[162:165], v[142:145], v[22:25]
	v_mfma_f32_16x16x32_bf16 v[22:25], v[158:161], v[250:253], v[22:25]
	s_setprio 0
	s_waitcnt vmcnt(0)
	s_barrier
	s_add_i32 s57, s57, 1
	s_cmp_lt_u32 s57, 44
	s_cbranch_scc1 .Lp9k_B_loop
